# combined: QKV epilogue ss-load hoist, nt on write-once f32 K/V stores, 8-deep K/V sample-memory conversion in prologue, skip redundant first-iteration vmcnt wait after drained epilogues
# speedup vs baseline: 1.0031x; 1.0031x over previous
; #define GAS __attribute__((address_space(1)))
; __device__ __forceinline__ unsigned pk_bf16(float lo, float hi) { f32x2_t v = {lo, hi}; bf16x2_t b = __builtin_convertvector(v, bf16x2_t); return __builtin_bit_cast(unsigned, b); }
; __device__ __forceinline__ void p0_prologue(const Frame& F, const Args& a) {
;     ...
;     { const GAS f32x4* src = (const GAS f32x4*)a.in[8]; GAS u32x4* dst = (GAS u32x4*)(ws + WS_VMTS); const int n8 = 2 * DB * NMEM * D / 8;
;       for (int i = F.bx * 512 + F.tid; i < n8; i += F.G * 512) { const f32x4 x = src[2 * i], y = src[2 * i + 1]; u32x4 w; w.x = pk_bf16(x[0], x[1]); w.y = pk_bf16(x[2], x[3]); w.z = pk_bf16(y[0], y[1]); w.w = pk_bf16(y[2], y[3]); dst[i] = w; } }
;     { const GAS f32x4* src = (const GAS f32x4*)a.in[7]; GAS u32x4* dst = (GAS u32x4*)(ws + WS_KMS); const int n8 = 2 * DB * NMEM * D / 8;
;       for (int i = F.bx * 512 + F.tid; i < n8; i += F.G * 512) { const f32x4 x = src[2 * i], y = src[2 * i + 1]; u32x4 w; w.x = pk_bf16(x[0], x[1]); w.y = pk_bf16(x[2], x[3]); w.z = pk_bf16(y[0], y[1]); w.w = pk_bf16(y[2], y[3]); dst[i] = w; } }
.LBB0_57:
	s_or_b64 exec, exec, s[4:5]
	s_mov_b32 s4, 0x200000
	v_cmp_gt_i32_e32 vcc, s4, v0
	s_and_saveexec_b64 s[4:5], vcc
	s_cbranch_execz .LBB0_62
	s_waitcnt lgkmcnt(0)
	s_cmp_eq_u32 s3, 0x100
	s_cbranch_scc0 .Lvk_generic
	v_lshlrev_b64 v[2:3], 4, v[0:1]
	v_lshl_add_u64 v[4:5], s[30:31], 0, v[2:3]
	v_lshlrev_b64 v[2:3], 5, v[0:1]
	v_lshl_add_u64 v[6:7], s[10:11], 0, v[2:3]
	v_lshl_add_u64 v[8:9], s[8:9], 0, v[2:3]
	s_mov_b64 s[14:15], 0x8c00000
	v_lshl_add_u64 v[10:11], v[4:5], 0, s[14:15]
	s_mov_b64 s[14:15], 0x6c00000
	v_lshl_add_u64 v[12:13], v[4:5], 0, s[14:15]
	s_mov_b64 s[14:15], 0x400000
	s_mov_b64 s[20:21], 0x200000
	s_mov_b32 s22, 8
.Lvk_loop:
	v_lshl_add_u64 v[14:15], v[6:7], 0, s[14:15]
	v_lshl_add_u64 v[16:17], v[8:9], 0, s[14:15]
	global_load_dwordx4 v[40:43], v[6:7], off
	global_load_dwordx4 v[44:47], v[6:7], off offset:16
	global_load_dwordx4 v[48:51], v[14:15], off
	global_load_dwordx4 v[52:55], v[14:15], off offset:16
	global_load_dwordx4 v[56:59], v[8:9], off
	global_load_dwordx4 v[60:63], v[8:9], off offset:16
	global_load_dwordx4 v[64:67], v[16:17], off
	global_load_dwordx4 v[68:71], v[16:17], off offset:16
	v_lshl_add_u64 v[18:19], v[10:11], 0, s[20:21]
	v_lshl_add_u64 v[20:21], v[12:13], 0, s[20:21]
	v_lshl_add_u64 v[6:7], v[14:15], 0, s[14:15]
	v_lshl_add_u64 v[8:9], v[16:17], 0, s[14:15]
	s_waitcnt vmcnt(6)
	v_cvt_pk_bf16_f32 v72, v40, v41
	v_cvt_pk_bf16_f32 v73, v42, v43
	v_cvt_pk_bf16_f32 v74, v44, v45
	v_cvt_pk_bf16_f32 v75, v46, v47
	global_store_dwordx4 v[10:11], v[72:75], off
	s_waitcnt vmcnt(5)
	v_cvt_pk_bf16_f32 v76, v48, v49
	v_cvt_pk_bf16_f32 v77, v50, v51
	v_cvt_pk_bf16_f32 v78, v52, v53
	v_cvt_pk_bf16_f32 v79, v54, v55
	global_store_dwordx4 v[18:19], v[76:79], off
	s_waitcnt vmcnt(4)
	v_cvt_pk_bf16_f32 v80, v56, v57
	v_cvt_pk_bf16_f32 v81, v58, v59
	v_cvt_pk_bf16_f32 v82, v60, v61
	v_cvt_pk_bf16_f32 v83, v62, v63
	global_store_dwordx4 v[12:13], v[80:83], off
	s_waitcnt vmcnt(3)
	v_cvt_pk_bf16_f32 v84, v64, v65
	v_cvt_pk_bf16_f32 v85, v66, v67
	v_cvt_pk_bf16_f32 v86, v68, v69
	v_cvt_pk_bf16_f32 v87, v70, v71
	global_store_dwordx4 v[20:21], v[84:87], off
	v_lshl_add_u64 v[10:11], v[18:19], 0, s[20:21]
	v_lshl_add_u64 v[12:13], v[20:21], 0, s[20:21]
	s_sub_i32 s22, s22, 1
	s_cmp_lg_u32 s22, 0
	s_cbranch_scc1 .Lvk_loop
	s_branch .LBB0_62
.Lvk_generic:
	s_lshl_b32 s12, s3, 9
	v_lshlrev_b64 v[2:3], 4, v[0:1]
	v_lshl_add_u64 v[4:5], s[30:31], 0, v[2:3]
	s_mov_b64 s[14:15], 0x8c00000
	s_ashr_i32 s13, s12, 31
	v_lshlrev_b32_e32 v2, 1, v0
	v_lshl_add_u64 v[6:7], v[4:5], 0, s[14:15]
	s_lshl_b64 s[14:15], s[12:13], 4
	s_lshl_b32 s13, s3, 10
	s_mov_b64 s[20:21], 0
	s_mov_b32 s22, 0x1fffff
	v_mov_b32_e32 v8, v2
	v_mov_b32_e32 v1, v0

; #define PG8_STAGE(bufoff, gbase, voff) do { _Pragma("unroll") for (int _i = 0; _i < 2; ++_i) \
;         __builtin_amdgcn_global_load_lds((const unsigned*)((const char*)(gbase) + (voff)[_i]), (LAS unsigned*)(lds + (bufoff) + ldsw + _i * 8192), 16, 0, 0); } while (0)
; #define PG8_LDA(dst, b, h) do { _Pragma("unroll") for (int m = 0; m < 4; ++m) _Pragma("unroll") for (int k = 0; k < 2; ++k) dst[m][k] = *(const LAS bf16x8*)(lds + PG8_SA(b, h) + aoff + m * 2048 + k * 1024); } while (0)
; #define PG8_LDB(dst, b, h) do { _Pragma("unroll") for (int n = 0; n < 2; ++n) _Pragma("unroll") for (int k = 0; k < 2; ++k) dst[n][k] = *(const LAS bf16x8*)(lds + PG8_SB(b, h) + boff + n * 2048 + k * 1024); } while (0)
; #define PG8_MMA(ai, bj, At, Bt) do { __builtin_amdgcn_s_setprio(1); _Pragma("unroll") for (int m = 0; m < 4; ++m) _Pragma("unroll") for (int n = 0; n < 2; ++n) _Pragma("unroll") for (int k = 0; k < 2; ++k) \
;         acc[ai][bj][m][n] = __builtin_amdgcn_mfma_f32_16x16x32_bf16(Bt[n][k], At[m][k], acc[ai][bj][m][n], 0, 0, 0); __builtin_amdgcn_s_setprio(0); } while (0)
; #define PG8_WAIT_V(n) asm volatile("s_waitcnt vmcnt(" #n ")" ::: "memory")
; #define PG8_WAIT_L(n) asm volatile("s_waitcnt lgkmcnt(" #n ")" ::: "memory")
; #define PG8_BAR __builtin_amdgcn_s_barrier()
; #define PG8_SCHED __builtin_amdgcn_sched_barrier(0)
; template <class Epi, class Sched>
; __device__ __forceinline__ void gemm_phase(LAS unsigned char* lds, const GemmP g, const Sched& S, const Epi& E, int tid) {
;     ...
;         for (int t = 0; t < nt; t += 2) {
;             const bool last = (t == nt - 2);
;             const char* a1 = cA + (size_t)(t + 1) * kstep;
;             const char* a2 = last ? nA : cA + (size_t)(t + 2) * kstep; const char* b2 = last ? nB : cB + (size_t)(t + 2) * kstep;
;             const char* a3 = a2 + kstep; const char* b3 = b2 + kstep;
;             PG8_LDB(B0, 0, 0); PG8_LDB(B1, 0, 1); PG8_SCHED; PG8_LDA(At, 0, 0); PG8_STAGE(PG8_SA(1, 1), a1 + hstepA, voffA);
;             PG8_WAIT_V(8); PG8_WAIT_L(0); PG8_BAR; PG8_MMA(0, 0, At, B0); PG8_MMA(0, 1, At, B1); PG8_BAR; PG8_SCHED;
;             PG8_LDA(At, 0, 1); PG8_STAGE(PG8_SB(0, 0), b2, voffB); PG8_STAGE(PG8_SB(0, 1), b2 + hstepB, voffB); PG8_STAGE(PG8_SA(0, 0), a2, voffA);
.LBB0_166:
	ds_read_b128 v[144:147], v157
	ds_read_b128 v[148:151], v157 offset:1024
	ds_read_b128 v[152:155], v157 offset:2048
	ds_read_b128 v[162:165], v157 offset:3072
	ds_read_b128 v[166:169], v158
	ds_read_b128 v[170:173], v158 offset:1024
	ds_read_b128 v[174:177], v158 offset:2048
	ds_read_b128 v[178:181], v158 offset:3072
	s_add_u32 s44, s4, 0xfffc0080
	s_addc_u32 s45, s5, -1
	s_cmp_eq_u32 s73, 12
	s_cselect_b32 s47, s37, s45
	s_cselect_b32 s46, s36, s44
	s_cselect_b32 s45, s39, s72
	s_cselect_b32 s44, s38, s71
	v_lshl_add_u64 v[214:215], s[4:5], 0, v[138:139]
	s_add_i32 m0, s53, 0xc000
	ds_read_b128 v[182:185], v159
	ds_read_b128 v[186:189], v159 offset:1024
	ds_read_b128 v[190:193], v159 offset:2048
	ds_read_b128 v[194:197], v159 offset:3072
	ds_read_b128 v[198:201], v159 offset:4096
	ds_read_b128 v[202:205], v159 offset:5120
	ds_read_b128 v[206:209], v159 offset:6144
	ds_read_b128 v[210:213], v159 offset:7168
	global_load_lds_dwordx4 v[214:215], off
	v_lshl_add_u64 v[214:215], s[4:5], 0, v[136:137]
	s_add_i32 m0, s53, 0xe000
	s_nop 0
	global_load_lds_dwordx4 v[214:215], off
	s_cmp_eq_u32 s73, -2
	s_cbranch_scc1 .Lfirstit_1
	s_waitcnt vmcnt(8)
.Lfirstit_1:
	s_waitcnt lgkmcnt(0)
	s_barrier
	s_setprio 1
	s_waitcnt lgkmcnt(0)
	v_mfma_f32_16x16x32_bf16 v[124:127], v[144:147], v[182:185], v[124:127]
	v_mfma_f32_16x16x32_bf16 v[120:123], v[152:155], v[182:185], v[120:123]
	v_mfma_f32_16x16x32_bf16 v[108:111], v[144:147], v[190:193], v[108:111]
	v_mfma_f32_16x16x32_bf16 v[104:107], v[152:155], v[190:193], v[104:107]
	v_mfma_f32_16x16x32_bf16 v[92:95], v[144:147], v[198:201], v[92:95]
	v_mfma_f32_16x16x32_bf16 v[88:91], v[152:155], v[198:201], v[88:91]
	v_mfma_f32_16x16x32_bf16 v[76:79], v[144:147], v[206:209], v[76:79]
	v_mfma_f32_16x16x32_bf16 v[72:75], v[152:155], v[206:209], v[72:75]
	v_mfma_f32_16x16x32_bf16 v[124:127], v[148:151], v[186:189], v[124:127]
	v_mfma_f32_16x16x32_bf16 v[120:123], v[162:165], v[186:189], v[120:123]
	v_mfma_f32_16x16x32_bf16 v[108:111], v[148:151], v[194:197], v[108:111]
	v_mfma_f32_16x16x32_bf16 v[104:107], v[162:165], v[194:197], v[104:107]
	v_mfma_f32_16x16x32_bf16 v[92:95], v[148:151], v[202:205], v[92:95]
	v_mfma_f32_16x16x32_bf16 v[88:91], v[162:165], v[202:205], v[88:91]
	v_mfma_f32_16x16x32_bf16 v[76:79], v[148:151], v[210:213], v[76:79]
	v_mfma_f32_16x16x32_bf16 v[72:75], v[162:165], v[210:213], v[72:75]
	s_setprio 0
	s_setprio 1
	v_mfma_f32_16x16x32_bf16 v[116:119], v[166:169], v[182:185], v[116:119]
	v_mfma_f32_16x16x32_bf16 v[112:115], v[174:177], v[182:185], v[112:115]
	v_mfma_f32_16x16x32_bf16 v[100:103], v[166:169], v[190:193], v[100:103]
	v_mfma_f32_16x16x32_bf16 v[96:99], v[174:177], v[190:193], v[96:99]
	v_mfma_f32_16x16x32_bf16 v[84:87], v[166:169], v[198:201], v[84:87]
	v_mfma_f32_16x16x32_bf16 v[80:83], v[174:177], v[198:201], v[80:83]
	v_mfma_f32_16x16x32_bf16 v[68:71], v[166:169], v[206:209], v[68:71]
	v_mfma_f32_16x16x32_bf16 v[64:67], v[174:177], v[206:209], v[64:67]
	v_mfma_f32_16x16x32_bf16 v[116:119], v[170:173], v[186:189], v[116:119]
	v_mfma_f32_16x16x32_bf16 v[112:115], v[178:181], v[186:189], v[112:115]
	v_mfma_f32_16x16x32_bf16 v[100:103], v[170:173], v[194:197], v[100:103]
	v_mfma_f32_16x16x32_bf16 v[96:99], v[178:181], v[194:197], v[96:99]
	v_mfma_f32_16x16x32_bf16 v[84:87], v[170:173], v[202:205], v[84:87]
	v_mfma_f32_16x16x32_bf16 v[80:83], v[178:181], v[202:205], v[80:83]
	v_mfma_f32_16x16x32_bf16 v[68:71], v[170:173], v[210:213], v[68:71]
	v_mfma_f32_16x16x32_bf16 v[64:67], v[178:181], v[210:213], v[64:67]
	s_setprio 0
	s_barrier
	s_add_i32 s74, s67, s52
	v_lshl_add_u64 v[214:215], s[44:45], 0, v[130:131]
	s_mov_b32 m0, s74
	ds_read_b128 v[182:185], v159 offset:16384
	ds_read_b128 v[186:189], v159 offset:17408
	ds_read_b128 v[190:193], v159 offset:18432
	ds_read_b128 v[194:197], v159 offset:19456
	ds_read_b128 v[198:201], v159 offset:20480
	ds_read_b128 v[202:205], v159 offset:21504
	ds_read_b128 v[206:209], v159 offset:22528
	ds_read_b128 v[210:213], v159 offset:23552
	global_load_lds_dwordx4 v[214:215], off
	s_add_i32 m0, s74, 0x2000
	s_add_u32 s74, s44, 0x40000
	v_lshl_add_u64 v[216:217], s[44:45], 0, v[134:135]
	s_addc_u32 s75, s45, 0
	s_add_i32 s76, s68, s52
	global_load_lds_dwordx4 v[216:217], off
	v_lshl_add_u64 v[218:219], s[74:75], 0, v[130:131]
	s_mov_b32 m0, s76
	v_lshl_add_u64 v[220:221], s[46:47], 0, v[132:133]
	global_load_lds_dwordx4 v[218:219], off
	v_lshl_add_u64 v[218:219], s[74:75], 0, v[134:135]
	s_add_i32 m0, s76, 0x2000
	s_nop 0
	global_load_lds_dwordx4 v[218:219], off
	v_lshl_add_u64 v[218:219], s[46:47], 0, v[128:129]
	s_mov_b32 m0, s53
	s_nop 0
	global_load_lds_dwordx4 v[218:219], off
	s_mov_b32 m0, s54
	s_nop 0
	global_load_lds_dwordx4 v[220:221], off
	s_waitcnt vmcnt(8)
	s_waitcnt lgkmcnt(0)
	s_barrier
; #define PG8_STAGE(bufoff, gbase, voff) do { _Pragma("unroll") for (int _i = 0; _i < 2; ++_i) \
;         __builtin_amdgcn_global_load_lds((const unsigned*)((const char*)(gbase) + (voff)[_i]), (LAS unsigned*)(lds + (bufoff) + ldsw + _i * 8192), 16, 0, 0); } while (0)
; #define PG8_LDA(dst, b, h) do { _Pragma("unroll") for (int m = 0; m < 4; ++m) _Pragma("unroll") for (int k = 0; k < 2; ++k) dst[m][k] = *(const LAS bf16x8*)(lds + PG8_SA(b, h) + aoff + m * 2048 + k * 1024); } while (0)
; #define PG8_LDB(dst, b, h) do { _Pragma("unroll") for (int n = 0; n < 2; ++n) _Pragma("unroll") for (int k = 0; k < 2; ++k) dst[n][k] = *(const LAS bf16x8*)(lds + PG8_SB(b, h) + boff + n * 2048 + k * 1024); } while (0)
; #define PG8_MMA(ai, bj, At, Bt) do { __builtin_amdgcn_s_setprio(1); _Pragma("unroll") for (int m = 0; m < 4; ++m) _Pragma("unroll") for (int n = 0; n < 2; ++n) _Pragma("unroll") for (int k = 0; k < 2; ++k) \
;         acc[ai][bj][m][n] = __builtin_amdgcn_mfma_f32_16x16x32_bf16(Bt[n][k], At[m][k], acc[ai][bj][m][n], 0, 0, 0); __builtin_amdgcn_s_setprio(0); } while (0)
; #define PG8_WAIT_V(n) asm volatile("s_waitcnt vmcnt(" #n ")" ::: "memory")
; #define PG8_WAIT_L(n) asm volatile("s_waitcnt lgkmcnt(" #n ")" ::: "memory")
; #define PG8_BAR __builtin_amdgcn_s_barrier()
; #define PG8_SCHED __builtin_amdgcn_sched_barrier(0)
; template <class Epi, class Sched>
; __device__ __forceinline__ void gemm_phase(LAS unsigned char* lds, const GemmP g, const Sched& S, const Epi& E, int tid) {
;     ...
;             PG8_WAIT_V(8); PG8_WAIT_L(0); PG8_BAR; PG8_MMA(1, 0, At, B0); PG8_MMA(1, 1, At, B1); PG8_BAR; PG8_SCHED;
;             PG8_LDB(B0, 1, 0); PG8_LDB(B1, 1, 1); PG8_SCHED; PG8_LDA(At, 1, 0); PG8_STAGE(PG8_SA(0, 1), a2 + hstepA, voffA);
;             PG8_WAIT_V(8); PG8_WAIT_L(0); PG8_BAR; PG8_MMA(0, 0, At, B0); PG8_MMA(0, 1, At, B1); PG8_BAR; PG8_SCHED;
	s_setprio 1
	s_waitcnt lgkmcnt(0)
	v_mfma_f32_16x16x32_bf16 v[60:63], v[144:147], v[182:185], v[60:63]
	v_mfma_f32_16x16x32_bf16 v[56:59], v[152:155], v[182:185], v[56:59]
	v_mfma_f32_16x16x32_bf16 v[44:47], v[144:147], v[190:193], v[44:47]
	v_mfma_f32_16x16x32_bf16 v[40:43], v[152:155], v[190:193], v[40:43]
	v_mfma_f32_16x16x32_bf16 v[28:31], v[144:147], v[198:201], v[28:31]
	v_mfma_f32_16x16x32_bf16 v[24:27], v[152:155], v[198:201], v[24:27]
	v_mfma_f32_16x16x32_bf16 v[12:15], v[144:147], v[206:209], v[12:15]
	v_mfma_f32_16x16x32_bf16 v[8:11], v[152:155], v[206:209], v[8:11]
	v_mfma_f32_16x16x32_bf16 v[60:63], v[148:151], v[186:189], v[60:63]
	v_mfma_f32_16x16x32_bf16 v[56:59], v[162:165], v[186:189], v[56:59]
	v_mfma_f32_16x16x32_bf16 v[44:47], v[148:151], v[194:197], v[44:47]
	v_mfma_f32_16x16x32_bf16 v[40:43], v[162:165], v[194:197], v[40:43]
	v_mfma_f32_16x16x32_bf16 v[28:31], v[148:151], v[202:205], v[28:31]
	v_mfma_f32_16x16x32_bf16 v[24:27], v[162:165], v[202:205], v[24:27]
	v_mfma_f32_16x16x32_bf16 v[12:15], v[148:151], v[210:213], v[12:15]
	v_mfma_f32_16x16x32_bf16 v[8:11], v[162:165], v[210:213], v[8:11]
	s_setprio 0
	s_setprio 1
	v_mfma_f32_16x16x32_bf16 v[52:55], v[166:169], v[182:185], v[52:55]
	v_mfma_f32_16x16x32_bf16 v[48:51], v[174:177], v[182:185], v[48:51]
	v_mfma_f32_16x16x32_bf16 v[36:39], v[166:169], v[190:193], v[36:39]
	v_mfma_f32_16x16x32_bf16 v[32:35], v[174:177], v[190:193], v[32:35]
	v_mfma_f32_16x16x32_bf16 v[20:23], v[166:169], v[198:201], v[20:23]
	v_mfma_f32_16x16x32_bf16 v[16:19], v[174:177], v[198:201], v[16:19]
	v_mfma_f32_16x16x32_bf16 v[4:7], v[166:169], v[206:209], v[4:7]
	v_mfma_f32_16x16x32_bf16 v[0:3], v[174:177], v[206:209], v[0:3]
	v_mfma_f32_16x16x32_bf16 v[52:55], v[170:173], v[186:189], v[52:55]
	v_mfma_f32_16x16x32_bf16 v[48:51], v[178:181], v[186:189], v[48:51]
	v_mfma_f32_16x16x32_bf16 v[36:39], v[170:173], v[194:197], v[36:39]
	v_mfma_f32_16x16x32_bf16 v[32:35], v[178:181], v[194:197], v[32:35]
	v_mfma_f32_16x16x32_bf16 v[20:23], v[170:173], v[202:205], v[20:23]
	v_mfma_f32_16x16x32_bf16 v[16:19], v[178:181], v[202:205], v[16:19]
	v_mfma_f32_16x16x32_bf16 v[4:7], v[170:173], v[210:213], v[4:7]
	v_mfma_f32_16x16x32_bf16 v[0:3], v[178:181], v[210:213], v[0:3]
	s_setprio 0
	s_barrier
	s_add_i32 s74, 0, 0x18000
	s_add_i32 s75, 0, 0x1c000
	v_add_u32_e32 v162, s74, v156
	v_add_u32_e32 v178, s75, v156
	ds_read_b128 v[144:147], v162
	ds_read_b128 v[148:151], v162 offset:1024
	ds_read_b128 v[152:155], v162 offset:2048
	ds_read_b128 v[162:165], v162 offset:3072
	ds_read_b128 v[166:169], v178
	ds_read_b128 v[170:173], v178 offset:1024
	ds_read_b128 v[174:177], v178 offset:2048
	ds_read_b128 v[178:181], v178 offset:3072
	s_add_u32 s46, s46, 0x40000
	s_addc_u32 s47, s47, 0
	s_mov_b32 m0, s55
	v_lshl_add_u64 v[222:223], s[46:47], 0, v[128:129]
	ds_read_b128 v[182:185], v159 offset:32768
	ds_read_b128 v[186:189], v159 offset:33792
	ds_read_b128 v[190:193], v159 offset:34816
	ds_read_b128 v[194:197], v159 offset:35840
	ds_read_b128 v[198:201], v159 offset:36864
	ds_read_b128 v[202:205], v159 offset:37888
	ds_read_b128 v[206:209], v159 offset:38912
	ds_read_b128 v[210:213], v159 offset:39936
	global_load_lds_dwordx4 v[222:223], off
	v_lshl_add_u64 v[222:223], s[46:47], 0, v[132:133]
	s_mov_b32 m0, s56
	s_nop 0
	global_load_lds_dwordx4 v[222:223], off
	s_waitcnt vmcnt(8)
	s_waitcnt lgkmcnt(0)
	s_barrier
	s_setprio 1
	s_waitcnt lgkmcnt(0)
	v_mfma_f32_16x16x32_bf16 v[124:127], v[144:147], v[182:185], v[124:127]
	v_mfma_f32_16x16x32_bf16 v[120:123], v[152:155], v[182:185], v[120:123]
	v_mfma_f32_16x16x32_bf16 v[108:111], v[144:147], v[190:193], v[108:111]
	v_mfma_f32_16x16x32_bf16 v[104:107], v[152:155], v[190:193], v[104:107]
	v_mfma_f32_16x16x32_bf16 v[92:95], v[144:147], v[198:201], v[92:95]
	v_mfma_f32_16x16x32_bf16 v[88:91], v[152:155], v[198:201], v[88:91]
	v_mfma_f32_16x16x32_bf16 v[76:79], v[144:147], v[206:209], v[76:79]
	v_mfma_f32_16x16x32_bf16 v[72:75], v[152:155], v[206:209], v[72:75]
	v_mfma_f32_16x16x32_bf16 v[124:127], v[148:151], v[186:189], v[124:127]
	v_mfma_f32_16x16x32_bf16 v[120:123], v[162:165], v[186:189], v[120:123]
	v_mfma_f32_16x16x32_bf16 v[108:111], v[148:151], v[194:197], v[108:111]
	v_mfma_f32_16x16x32_bf16 v[104:107], v[162:165], v[194:197], v[104:107]
	v_mfma_f32_16x16x32_bf16 v[92:95], v[148:151], v[202:205], v[92:95]
	v_mfma_f32_16x16x32_bf16 v[88:91], v[162:165], v[202:205], v[88:91]
	v_mfma_f32_16x16x32_bf16 v[76:79], v[148:151], v[210:213], v[76:79]
	v_mfma_f32_16x16x32_bf16 v[72:75], v[162:165], v[210:213], v[72:75]
	s_setprio 0
	s_setprio 1
	v_mfma_f32_16x16x32_bf16 v[116:119], v[166:169], v[182:185], v[116:119]
	v_mfma_f32_16x16x32_bf16 v[112:115], v[174:177], v[182:185], v[112:115]
	v_mfma_f32_16x16x32_bf16 v[100:103], v[166:169], v[190:193], v[100:103]
	v_mfma_f32_16x16x32_bf16 v[96:99], v[174:177], v[190:193], v[96:99]
	v_mfma_f32_16x16x32_bf16 v[84:87], v[166:169], v[198:201], v[84:87]
	v_mfma_f32_16x16x32_bf16 v[80:83], v[174:177], v[198:201], v[80:83]
	v_mfma_f32_16x16x32_bf16 v[68:71], v[166:169], v[206:209], v[68:71]
	v_mfma_f32_16x16x32_bf16 v[64:67], v[174:177], v[206:209], v[64:67]
	v_mfma_f32_16x16x32_bf16 v[116:119], v[170:173], v[186:189], v[116:119]
	v_mfma_f32_16x16x32_bf16 v[112:115], v[178:181], v[186:189], v[112:115]
	v_mfma_f32_16x16x32_bf16 v[100:103], v[170:173], v[194:197], v[100:103]
	v_mfma_f32_16x16x32_bf16 v[96:99], v[178:181], v[194:197], v[96:99]
	v_mfma_f32_16x16x32_bf16 v[84:87], v[170:173], v[202:205], v[84:87]
	v_mfma_f32_16x16x32_bf16 v[80:83], v[178:181], v[202:205], v[80:83]
	v_mfma_f32_16x16x32_bf16 v[68:71], v[170:173], v[210:213], v[68:71]
	v_mfma_f32_16x16x32_bf16 v[64:67], v[178:181], v[210:213], v[64:67]
	s_setprio 0
	s_barrier
; #define PG8_STAGE(bufoff, gbase, voff) do { _Pragma("unroll") for (int _i = 0; _i < 2; ++_i) \
;         __builtin_amdgcn_global_load_lds((const unsigned*)((const char*)(gbase) + (voff)[_i]), (LAS unsigned*)(lds + (bufoff) + ldsw + _i * 8192), 16, 0, 0); } while (0)
; #define PG8_LDA(dst, b, h) do { _Pragma("unroll") for (int m = 0; m < 4; ++m) _Pragma("unroll") for (int k = 0; k < 2; ++k) dst[m][k] = *(const LAS bf16x8*)(lds + PG8_SA(b, h) + aoff + m * 2048 + k * 1024); } while (0)
; #define PG8_MMA(ai, bj, At, Bt) do { __builtin_amdgcn_s_setprio(1); _Pragma("unroll") for (int m = 0; m < 4; ++m) _Pragma("unroll") for (int n = 0; n < 2; ++n) _Pragma("unroll") for (int k = 0; k < 2; ++k) \
;         acc[ai][bj][m][n] = __builtin_amdgcn_mfma_f32_16x16x32_bf16(Bt[n][k], At[m][k], acc[ai][bj][m][n], 0, 0, 0); __builtin_amdgcn_s_setprio(0); } while (0)
; #define PG8_WAIT_V(n) asm volatile("s_waitcnt vmcnt(" #n ")" ::: "memory")
; #define PG8_WAIT_L(n) asm volatile("s_waitcnt lgkmcnt(" #n ")" ::: "memory")
; #define PG8_BAR __builtin_amdgcn_s_barrier()
; #define PG8_SCHED __builtin_amdgcn_sched_barrier(0)
; template <class Epi, class Sched>
; __device__ __forceinline__ void gemm_phase(LAS unsigned char* lds, const GemmP g, const Sched& S, const Epi& E, int tid) {
;     ...
;             PG8_LDA(At, 1, 1); PG8_STAGE(PG8_SB(1, 0), b3, voffB); PG8_STAGE(PG8_SB(1, 1), b3 + hstepB, voffB); PG8_STAGE(PG8_SA(1, 0), a3, voffA);
;             PG8_WAIT_V(8); PG8_WAIT_L(0); PG8_BAR; PG8_MMA(1, 0, At, B0); PG8_MMA(1, 1, At, B1); PG8_BAR; PG8_SCHED;
;         }
;         if (wr == 0) PG8_BAR;
	s_add_i32 s46, s74, s52
	v_lshl_add_u64 v[214:215], v[214:215], 0, s[14:15]
	s_mov_b32 m0, s46
	ds_read_b128 v[182:185], v159 offset:49152
	ds_read_b128 v[186:189], v159 offset:50176
	ds_read_b128 v[190:193], v159 offset:51200
	ds_read_b128 v[194:197], v159 offset:52224
	ds_read_b128 v[198:201], v159 offset:53248
	ds_read_b128 v[202:205], v159 offset:54272
	ds_read_b128 v[206:209], v159 offset:55296
	ds_read_b128 v[210:213], v159 offset:56320
	global_load_lds_dwordx4 v[214:215], off
	s_add_i32 m0, s46, 0x2000
	s_add_u32 s44, s44, 0x40080
	v_lshl_add_u64 v[214:215], v[216:217], 0, s[14:15]
	s_addc_u32 s45, s45, 0
	s_add_i32 s46, s75, s52
	global_load_lds_dwordx4 v[214:215], off
	v_lshl_add_u64 v[214:215], s[44:45], 0, v[130:131]
	s_mov_b32 m0, s46
	s_nop 0
	global_load_lds_dwordx4 v[214:215], off
	v_lshl_add_u64 v[214:215], s[44:45], 0, v[134:135]
	s_add_i32 m0, s46, 0x2000
	s_nop 0
	global_load_lds_dwordx4 v[214:215], off
	v_lshl_add_u64 v[214:215], v[218:219], 0, s[14:15]
	s_mov_b32 m0, s62
	s_nop 0
	global_load_lds_dwordx4 v[214:215], off
	v_lshl_add_u64 v[214:215], v[220:221], 0, s[14:15]
	s_mov_b32 m0, s63
	s_nop 0
	global_load_lds_dwordx4 v[214:215], off
	s_waitcnt vmcnt(8)
	s_waitcnt lgkmcnt(0)
	s_barrier
	s_setprio 1
	s_waitcnt lgkmcnt(0)
	v_mfma_f32_16x16x32_bf16 v[60:63], v[144:147], v[182:185], v[60:63]
	v_mfma_f32_16x16x32_bf16 v[56:59], v[152:155], v[182:185], v[56:59]
	v_mfma_f32_16x16x32_bf16 v[44:47], v[144:147], v[190:193], v[44:47]
	v_mfma_f32_16x16x32_bf16 v[40:43], v[152:155], v[190:193], v[40:43]
	v_mfma_f32_16x16x32_bf16 v[28:31], v[144:147], v[198:201], v[28:31]
	v_mfma_f32_16x16x32_bf16 v[24:27], v[152:155], v[198:201], v[24:27]
	v_mfma_f32_16x16x32_bf16 v[12:15], v[144:147], v[206:209], v[12:15]
	v_mfma_f32_16x16x32_bf16 v[8:11], v[152:155], v[206:209], v[8:11]
	v_mfma_f32_16x16x32_bf16 v[60:63], v[148:151], v[186:189], v[60:63]
	v_mfma_f32_16x16x32_bf16 v[56:59], v[162:165], v[186:189], v[56:59]
	v_mfma_f32_16x16x32_bf16 v[44:47], v[148:151], v[194:197], v[44:47]
	v_mfma_f32_16x16x32_bf16 v[40:43], v[162:165], v[194:197], v[40:43]
	v_mfma_f32_16x16x32_bf16 v[28:31], v[148:151], v[202:205], v[28:31]
	v_mfma_f32_16x16x32_bf16 v[24:27], v[162:165], v[202:205], v[24:27]
	v_mfma_f32_16x16x32_bf16 v[12:15], v[148:151], v[210:213], v[12:15]
	v_mfma_f32_16x16x32_bf16 v[8:11], v[162:165], v[210:213], v[8:11]
	s_setprio 0
	s_setprio 1
	v_mfma_f32_16x16x32_bf16 v[52:55], v[166:169], v[182:185], v[52:55]
	v_mfma_f32_16x16x32_bf16 v[48:51], v[174:177], v[182:185], v[48:51]
	v_mfma_f32_16x16x32_bf16 v[36:39], v[166:169], v[190:193], v[36:39]
	v_mfma_f32_16x16x32_bf16 v[32:35], v[174:177], v[190:193], v[32:35]
	v_mfma_f32_16x16x32_bf16 v[20:23], v[166:169], v[198:201], v[20:23]
	v_mfma_f32_16x16x32_bf16 v[16:19], v[174:177], v[198:201], v[16:19]
	v_mfma_f32_16x16x32_bf16 v[4:7], v[166:169], v[206:209], v[4:7]
	v_mfma_f32_16x16x32_bf16 v[0:3], v[174:177], v[206:209], v[0:3]
	v_mfma_f32_16x16x32_bf16 v[52:55], v[170:173], v[186:189], v[52:55]
	v_mfma_f32_16x16x32_bf16 v[48:51], v[178:181], v[186:189], v[48:51]
	v_mfma_f32_16x16x32_bf16 v[36:39], v[170:173], v[194:197], v[36:39]
	v_mfma_f32_16x16x32_bf16 v[32:35], v[178:181], v[194:197], v[32:35]
	v_mfma_f32_16x16x32_bf16 v[20:23], v[170:173], v[202:205], v[20:23]
	v_mfma_f32_16x16x32_bf16 v[16:19], v[178:181], v[202:205], v[16:19]
	v_mfma_f32_16x16x32_bf16 v[4:7], v[170:173], v[210:213], v[4:7]
	v_mfma_f32_16x16x32_bf16 v[0:3], v[178:181], v[210:213], v[0:3]
	s_setprio 0
	s_barrier
	s_add_i32 s73, s73, 2
	s_add_u32 s71, s71, 0x100
	s_addc_u32 s72, s72, 0
	s_add_u32 s4, s4, 0x100
	s_addc_u32 s5, s5, 0
	s_cmp_gt_u32 s73, 13
	s_cbranch_scc0 .LBB0_166
	s_and_b64 vcc, exec, s[16:17]
	s_cbranch_vccz .LBB0_169
	s_barrier

; #define PG8_STAGE(bufoff, gbase, voff) do { _Pragma("unroll") for (int _i = 0; _i < 2; ++_i) \
;         __builtin_amdgcn_global_load_lds((const unsigned*)((const char*)(gbase) + (voff)[_i]), (LAS unsigned*)(lds + (bufoff) + ldsw + _i * 8192), 16, 0, 0); } while (0)
; #define PG8_LDA(dst, b, h) do { _Pragma("unroll") for (int m = 0; m < 4; ++m) _Pragma("unroll") for (int k = 0; k < 2; ++k) dst[m][k] = *(const LAS bf16x8*)(lds + PG8_SA(b, h) + aoff + m * 2048 + k * 1024); } while (0)
; #define PG8_LDB(dst, b, h) do { _Pragma("unroll") for (int n = 0; n < 2; ++n) _Pragma("unroll") for (int k = 0; k < 2; ++k) dst[n][k] = *(const LAS bf16x8*)(lds + PG8_SB(b, h) + boff + n * 2048 + k * 1024); } while (0)
; #define PG8_MMA(ai, bj, At, Bt) do { __builtin_amdgcn_s_setprio(1); _Pragma("unroll") for (int m = 0; m < 4; ++m) _Pragma("unroll") for (int n = 0; n < 2; ++n) _Pragma("unroll") for (int k = 0; k < 2; ++k) \
;         acc[ai][bj][m][n] = __builtin_amdgcn_mfma_f32_16x16x32_bf16(Bt[n][k], At[m][k], acc[ai][bj][m][n], 0, 0, 0); __builtin_amdgcn_s_setprio(0); } while (0)
; #define PG8_WAIT_V(n) asm volatile("s_waitcnt vmcnt(" #n ")" ::: "memory")
; #define PG8_WAIT_L(n) asm volatile("s_waitcnt lgkmcnt(" #n ")" ::: "memory")
; #define PG8_BAR __builtin_amdgcn_s_barrier()
; #define PG8_SCHED __builtin_amdgcn_sched_barrier(0)
; template <class Epi, class Sched>
; __device__ __forceinline__ void gemm_phase(LAS unsigned char* lds, const GemmP g, const Sched& S, const Epi& E, int tid) {
;     ...
;         for (int t = 0; t < nt; t += 2) {
;             const bool last = (t == nt - 2);
;             const char* a1 = cA + (size_t)(t + 1) * kstep;
;             const char* a2 = last ? nA : cA + (size_t)(t + 2) * kstep; const char* b2 = last ? nB : cB + (size_t)(t + 2) * kstep;
;             const char* a3 = a2 + kstep; const char* b3 = b2 + kstep;
;             PG8_LDB(B0, 0, 0); PG8_LDB(B1, 0, 1); PG8_SCHED; PG8_LDA(At, 0, 0); PG8_STAGE(PG8_SA(1, 1), a1 + hstepA, voffA);
;             PG8_WAIT_V(8); PG8_WAIT_L(0); PG8_BAR; PG8_MMA(0, 0, At, B0); PG8_MMA(0, 1, At, B1); PG8_BAR; PG8_SCHED;
;             PG8_LDA(At, 0, 1); PG8_STAGE(PG8_SB(0, 0), b2, voffB); PG8_STAGE(PG8_SB(0, 1), b2 + hstepB, voffB); PG8_STAGE(PG8_SA(0, 0), a2, voffA);
.LBB0_445:
	ds_read_b128 v[128:131], v209
	ds_read_b128 v[132:135], v209 offset:1024
	ds_read_b128 v[136:139], v209 offset:2048
	ds_read_b128 v[140:143], v209 offset:3072
	ds_read_b128 v[144:147], v210
	ds_read_b128 v[148:151], v210 offset:1024
	ds_read_b128 v[152:155], v210 offset:2048
	ds_read_b128 v[156:159], v210 offset:3072
	s_add_u32 s6, s4, 0xfffc0080
	s_addc_u32 s7, s5, -1
	s_cmp_eq_u32 s14, 12
	s_cselect_b32 s9, s51, s7
	s_cselect_b32 s8, s50, s6
	s_cselect_b32 s7, s53, s13
	s_cselect_b32 s6, s52, s12
	v_lshl_add_u64 v[212:213], s[4:5], 0, v[198:199]
	s_add_i32 m0, s75, 0xc000
	ds_read_b128 v[160:163], v211
	ds_read_b128 v[164:167], v211 offset:1024
	ds_read_b128 v[168:171], v211 offset:2048
	ds_read_b128 v[172:175], v211 offset:3072
	ds_read_b128 v[176:179], v211 offset:4096
	ds_read_b128 v[180:183], v211 offset:5120
	ds_read_b128 v[184:187], v211 offset:6144
	ds_read_b128 v[204:207], v211 offset:7168
	global_load_lds_dwordx4 v[212:213], off
	v_lshl_add_u64 v[212:213], s[4:5], 0, v[196:197]
	s_add_i32 m0, s75, 0xe000
	s_nop 0
	global_load_lds_dwordx4 v[212:213], off
	s_cmp_eq_u32 s14, -2
	s_cbranch_scc1 .Lfirstit_2
	s_waitcnt vmcnt(8)
.Lfirstit_2:
	s_waitcnt lgkmcnt(0)
	s_barrier
	s_setprio 1
	s_waitcnt lgkmcnt(0)
	v_mfma_f32_16x16x32_bf16 v[124:127], v[128:131], v[160:163], v[124:127]
	v_mfma_f32_16x16x32_bf16 v[120:123], v[136:139], v[160:163], v[120:123]
	v_mfma_f32_16x16x32_bf16 v[116:119], v[128:131], v[168:171], v[116:119]
	v_mfma_f32_16x16x32_bf16 v[112:115], v[136:139], v[168:171], v[112:115]
	v_mfma_f32_16x16x32_bf16 v[108:111], v[128:131], v[176:179], v[108:111]
	v_mfma_f32_16x16x32_bf16 v[104:107], v[136:139], v[176:179], v[104:107]
	v_mfma_f32_16x16x32_bf16 v[100:103], v[128:131], v[184:187], v[100:103]
	v_mfma_f32_16x16x32_bf16 v[96:99], v[136:139], v[184:187], v[96:99]
	v_mfma_f32_16x16x32_bf16 v[124:127], v[132:135], v[164:167], v[124:127]
	v_mfma_f32_16x16x32_bf16 v[120:123], v[140:143], v[164:167], v[120:123]
	v_mfma_f32_16x16x32_bf16 v[116:119], v[132:135], v[172:175], v[116:119]
	v_mfma_f32_16x16x32_bf16 v[112:115], v[140:143], v[172:175], v[112:115]
	v_mfma_f32_16x16x32_bf16 v[108:111], v[132:135], v[180:183], v[108:111]
	v_mfma_f32_16x16x32_bf16 v[104:107], v[140:143], v[180:183], v[104:107]
	v_mfma_f32_16x16x32_bf16 v[100:103], v[132:135], v[204:207], v[100:103]
	v_mfma_f32_16x16x32_bf16 v[96:99], v[140:143], v[204:207], v[96:99]
	s_setprio 0
	s_setprio 1
	v_mfma_f32_16x16x32_bf16 v[68:71], v[144:147], v[160:163], v[68:71]
	v_mfma_f32_16x16x32_bf16 v[60:63], v[152:155], v[160:163], v[60:63]
	v_mfma_f32_16x16x32_bf16 v[52:55], v[144:147], v[168:171], v[52:55]
	v_mfma_f32_16x16x32_bf16 v[48:51], v[152:155], v[168:171], v[48:51]
	v_mfma_f32_16x16x32_bf16 v[44:47], v[144:147], v[176:179], v[44:47]
	v_mfma_f32_16x16x32_bf16 v[40:43], v[152:155], v[176:179], v[40:43]
	v_mfma_f32_16x16x32_bf16 v[36:39], v[144:147], v[184:187], v[36:39]
	v_mfma_f32_16x16x32_bf16 v[32:35], v[152:155], v[184:187], v[32:35]
	v_mfma_f32_16x16x32_bf16 v[68:71], v[148:151], v[164:167], v[68:71]
	v_mfma_f32_16x16x32_bf16 v[60:63], v[156:159], v[164:167], v[60:63]
	v_mfma_f32_16x16x32_bf16 v[52:55], v[148:151], v[172:175], v[52:55]
	v_mfma_f32_16x16x32_bf16 v[48:51], v[156:159], v[172:175], v[48:51]
	v_mfma_f32_16x16x32_bf16 v[44:47], v[148:151], v[180:183], v[44:47]
	v_mfma_f32_16x16x32_bf16 v[40:43], v[156:159], v[180:183], v[40:43]
	v_mfma_f32_16x16x32_bf16 v[36:39], v[148:151], v[204:207], v[36:39]
	v_mfma_f32_16x16x32_bf16 v[32:35], v[156:159], v[204:207], v[32:35]
	s_setprio 0
	s_barrier
	s_add_i32 s15, s86, s74
	v_lshl_add_u64 v[212:213], s[6:7], 0, v[190:191]
	s_mov_b32 m0, s15
	ds_read_b128 v[160:163], v211 offset:16384
	ds_read_b128 v[164:167], v211 offset:17408
	ds_read_b128 v[168:171], v211 offset:18432
	ds_read_b128 v[172:175], v211 offset:19456
	ds_read_b128 v[176:179], v211 offset:20480
	ds_read_b128 v[180:183], v211 offset:21504
	ds_read_b128 v[184:187], v211 offset:22528
	ds_read_b128 v[204:207], v211 offset:23552
	global_load_lds_dwordx4 v[212:213], off
	s_add_i32 m0, s15, 0x2000
	s_add_u32 s16, s6, 0x40000
	v_lshl_add_u64 v[214:215], s[6:7], 0, v[194:195]
	s_addc_u32 s17, s7, 0
	s_add_i32 s15, s87, s74
	global_load_lds_dwordx4 v[214:215], off
	v_lshl_add_u64 v[216:217], s[16:17], 0, v[190:191]
	s_mov_b32 m0, s15
	v_lshl_add_u64 v[218:219], s[8:9], 0, v[192:193]
	global_load_lds_dwordx4 v[216:217], off
	v_lshl_add_u64 v[216:217], s[16:17], 0, v[194:195]
	s_add_i32 m0, s15, 0x2000
	s_nop 0
	global_load_lds_dwordx4 v[216:217], off
	v_lshl_add_u64 v[216:217], s[8:9], 0, v[188:189]
	s_mov_b32 m0, s75
	s_nop 0
	global_load_lds_dwordx4 v[216:217], off
	s_mov_b32 m0, s76
	s_nop 0
	global_load_lds_dwordx4 v[218:219], off
	s_waitcnt vmcnt(8)
	s_waitcnt lgkmcnt(0)
	s_barrier
; #define PG8_STAGE(bufoff, gbase, voff) do { _Pragma("unroll") for (int _i = 0; _i < 2; ++_i) \
;         __builtin_amdgcn_global_load_lds((const unsigned*)((const char*)(gbase) + (voff)[_i]), (LAS unsigned*)(lds + (bufoff) + ldsw + _i * 8192), 16, 0, 0); } while (0)
; #define PG8_LDA(dst, b, h) do { _Pragma("unroll") for (int m = 0; m < 4; ++m) _Pragma("unroll") for (int k = 0; k < 2; ++k) dst[m][k] = *(const LAS bf16x8*)(lds + PG8_SA(b, h) + aoff + m * 2048 + k * 1024); } while (0)
; #define PG8_LDB(dst, b, h) do { _Pragma("unroll") for (int n = 0; n < 2; ++n) _Pragma("unroll") for (int k = 0; k < 2; ++k) dst[n][k] = *(const LAS bf16x8*)(lds + PG8_SB(b, h) + boff + n * 2048 + k * 1024); } while (0)
; #define PG8_MMA(ai, bj, At, Bt) do { __builtin_amdgcn_s_setprio(1); _Pragma("unroll") for (int m = 0; m < 4; ++m) _Pragma("unroll") for (int n = 0; n < 2; ++n) _Pragma("unroll") for (int k = 0; k < 2; ++k) \
;         acc[ai][bj][m][n] = __builtin_amdgcn_mfma_f32_16x16x32_bf16(Bt[n][k], At[m][k], acc[ai][bj][m][n], 0, 0, 0); __builtin_amdgcn_s_setprio(0); } while (0)
; #define PG8_WAIT_V(n) asm volatile("s_waitcnt vmcnt(" #n ")" ::: "memory")
; #define PG8_WAIT_L(n) asm volatile("s_waitcnt lgkmcnt(" #n ")" ::: "memory")
; #define PG8_BAR __builtin_amdgcn_s_barrier()
; #define PG8_SCHED __builtin_amdgcn_sched_barrier(0)
; template <class Epi, class Sched>
; __device__ __forceinline__ void gemm_phase(LAS unsigned char* lds, const GemmP g, const Sched& S, const Epi& E, int tid) {
;     ...
;             PG8_WAIT_V(8); PG8_WAIT_L(0); PG8_BAR; PG8_MMA(1, 0, At, B0); PG8_MMA(1, 1, At, B1); PG8_BAR; PG8_SCHED;
;             PG8_LDB(B0, 1, 0); PG8_LDB(B1, 1, 1); PG8_SCHED; PG8_LDA(At, 1, 0); PG8_STAGE(PG8_SA(0, 1), a2 + hstepA, voffA);
;             PG8_WAIT_V(8); PG8_WAIT_L(0); PG8_BAR; PG8_MMA(0, 0, At, B0); PG8_MMA(0, 1, At, B1); PG8_BAR; PG8_SCHED;
	s_setprio 1
	s_waitcnt lgkmcnt(0)
	v_mfma_f32_16x16x32_bf16 v[92:95], v[128:131], v[160:163], v[92:95]
	v_mfma_f32_16x16x32_bf16 v[88:91], v[136:139], v[160:163], v[88:91]
	v_mfma_f32_16x16x32_bf16 v[84:87], v[128:131], v[168:171], v[84:87]
	v_mfma_f32_16x16x32_bf16 v[80:83], v[136:139], v[168:171], v[80:83]
	v_mfma_f32_16x16x32_bf16 v[76:79], v[128:131], v[176:179], v[76:79]
	v_mfma_f32_16x16x32_bf16 v[72:75], v[136:139], v[176:179], v[72:75]
	v_mfma_f32_16x16x32_bf16 v[64:67], v[128:131], v[184:187], v[64:67]
	v_mfma_f32_16x16x32_bf16 v[56:59], v[136:139], v[184:187], v[56:59]
	v_mfma_f32_16x16x32_bf16 v[92:95], v[132:135], v[164:167], v[92:95]
	v_mfma_f32_16x16x32_bf16 v[88:91], v[140:143], v[164:167], v[88:91]
	v_mfma_f32_16x16x32_bf16 v[84:87], v[132:135], v[172:175], v[84:87]
	v_mfma_f32_16x16x32_bf16 v[80:83], v[140:143], v[172:175], v[80:83]
	v_mfma_f32_16x16x32_bf16 v[76:79], v[132:135], v[180:183], v[76:79]
	v_mfma_f32_16x16x32_bf16 v[72:75], v[140:143], v[180:183], v[72:75]
	v_mfma_f32_16x16x32_bf16 v[64:67], v[132:135], v[204:207], v[64:67]
	v_mfma_f32_16x16x32_bf16 v[56:59], v[140:143], v[204:207], v[56:59]
	s_setprio 0
	s_setprio 1
	v_mfma_f32_16x16x32_bf16 v[28:31], v[144:147], v[160:163], v[28:31]
	v_mfma_f32_16x16x32_bf16 v[24:27], v[152:155], v[160:163], v[24:27]
	v_mfma_f32_16x16x32_bf16 v[20:23], v[144:147], v[168:171], v[20:23]
	v_mfma_f32_16x16x32_bf16 v[16:19], v[152:155], v[168:171], v[16:19]
	v_mfma_f32_16x16x32_bf16 v[12:15], v[144:147], v[176:179], v[12:15]
	v_mfma_f32_16x16x32_bf16 v[8:11], v[152:155], v[176:179], v[8:11]
	v_mfma_f32_16x16x32_bf16 v[4:7], v[144:147], v[184:187], v[4:7]
	v_mfma_f32_16x16x32_bf16 v[0:3], v[152:155], v[184:187], v[0:3]
	v_mfma_f32_16x16x32_bf16 v[28:31], v[148:151], v[164:167], v[28:31]
	v_mfma_f32_16x16x32_bf16 v[24:27], v[156:159], v[164:167], v[24:27]
	v_mfma_f32_16x16x32_bf16 v[20:23], v[148:151], v[172:175], v[20:23]
	v_mfma_f32_16x16x32_bf16 v[16:19], v[156:159], v[172:175], v[16:19]
	v_mfma_f32_16x16x32_bf16 v[12:15], v[148:151], v[180:183], v[12:15]
	v_mfma_f32_16x16x32_bf16 v[8:11], v[156:159], v[180:183], v[8:11]
	v_mfma_f32_16x16x32_bf16 v[4:7], v[148:151], v[204:207], v[4:7]
	v_mfma_f32_16x16x32_bf16 v[0:3], v[156:159], v[204:207], v[0:3]
	s_setprio 0
	s_barrier
	s_add_i32 s15, 0, 0x18000
	s_add_i32 s16, 0, 0x1c000
	v_add_u32_e32 v140, s15, v208
	v_add_u32_e32 v156, s16, v208
	ds_read_b128 v[128:131], v140
	ds_read_b128 v[132:135], v140 offset:1024
	ds_read_b128 v[136:139], v140 offset:2048
	ds_read_b128 v[140:143], v140 offset:3072
	ds_read_b128 v[144:147], v156
	ds_read_b128 v[148:151], v156 offset:1024
	ds_read_b128 v[152:155], v156 offset:2048
	ds_read_b128 v[156:159], v156 offset:3072
	s_add_u32 s8, s8, 0x40000
	s_addc_u32 s9, s9, 0
	s_mov_b32 m0, s77
	v_lshl_add_u64 v[220:221], s[8:9], 0, v[188:189]
	ds_read_b128 v[160:163], v211 offset:32768
	ds_read_b128 v[164:167], v211 offset:33792
	ds_read_b128 v[168:171], v211 offset:34816
	ds_read_b128 v[172:175], v211 offset:35840
	ds_read_b128 v[176:179], v211 offset:36864
	ds_read_b128 v[180:183], v211 offset:37888
	ds_read_b128 v[184:187], v211 offset:38912
	ds_read_b128 v[204:207], v211 offset:39936
	global_load_lds_dwordx4 v[220:221], off
	v_lshl_add_u64 v[220:221], s[8:9], 0, v[192:193]
	s_mov_b32 m0, s78
	s_nop 0
	global_load_lds_dwordx4 v[220:221], off
	s_waitcnt vmcnt(8)
	s_waitcnt lgkmcnt(0)
	s_barrier
	s_setprio 1
	s_waitcnt lgkmcnt(0)
	v_mfma_f32_16x16x32_bf16 v[124:127], v[128:131], v[160:163], v[124:127]
	v_mfma_f32_16x16x32_bf16 v[120:123], v[136:139], v[160:163], v[120:123]
	v_mfma_f32_16x16x32_bf16 v[116:119], v[128:131], v[168:171], v[116:119]
	v_mfma_f32_16x16x32_bf16 v[112:115], v[136:139], v[168:171], v[112:115]
	v_mfma_f32_16x16x32_bf16 v[108:111], v[128:131], v[176:179], v[108:111]
	v_mfma_f32_16x16x32_bf16 v[104:107], v[136:139], v[176:179], v[104:107]
	v_mfma_f32_16x16x32_bf16 v[100:103], v[128:131], v[184:187], v[100:103]
	v_mfma_f32_16x16x32_bf16 v[96:99], v[136:139], v[184:187], v[96:99]
	v_mfma_f32_16x16x32_bf16 v[124:127], v[132:135], v[164:167], v[124:127]
	v_mfma_f32_16x16x32_bf16 v[120:123], v[140:143], v[164:167], v[120:123]
	v_mfma_f32_16x16x32_bf16 v[116:119], v[132:135], v[172:175], v[116:119]
	v_mfma_f32_16x16x32_bf16 v[112:115], v[140:143], v[172:175], v[112:115]
	v_mfma_f32_16x16x32_bf16 v[108:111], v[132:135], v[180:183], v[108:111]
	v_mfma_f32_16x16x32_bf16 v[104:107], v[140:143], v[180:183], v[104:107]
	v_mfma_f32_16x16x32_bf16 v[100:103], v[132:135], v[204:207], v[100:103]
	v_mfma_f32_16x16x32_bf16 v[96:99], v[140:143], v[204:207], v[96:99]
	s_setprio 0
	s_setprio 1
	v_mfma_f32_16x16x32_bf16 v[68:71], v[144:147], v[160:163], v[68:71]
	v_mfma_f32_16x16x32_bf16 v[60:63], v[152:155], v[160:163], v[60:63]
	v_mfma_f32_16x16x32_bf16 v[52:55], v[144:147], v[168:171], v[52:55]
	v_mfma_f32_16x16x32_bf16 v[48:51], v[152:155], v[168:171], v[48:51]
	v_mfma_f32_16x16x32_bf16 v[44:47], v[144:147], v[176:179], v[44:47]
	v_mfma_f32_16x16x32_bf16 v[40:43], v[152:155], v[176:179], v[40:43]
	v_mfma_f32_16x16x32_bf16 v[36:39], v[144:147], v[184:187], v[36:39]
	v_mfma_f32_16x16x32_bf16 v[32:35], v[152:155], v[184:187], v[32:35]
	v_mfma_f32_16x16x32_bf16 v[68:71], v[148:151], v[164:167], v[68:71]
	v_mfma_f32_16x16x32_bf16 v[60:63], v[156:159], v[164:167], v[60:63]
	v_mfma_f32_16x16x32_bf16 v[52:55], v[148:151], v[172:175], v[52:55]
	v_mfma_f32_16x16x32_bf16 v[48:51], v[156:159], v[172:175], v[48:51]
	v_mfma_f32_16x16x32_bf16 v[44:47], v[148:151], v[180:183], v[44:47]
	v_mfma_f32_16x16x32_bf16 v[40:43], v[156:159], v[180:183], v[40:43]
	v_mfma_f32_16x16x32_bf16 v[36:39], v[148:151], v[204:207], v[36:39]
	v_mfma_f32_16x16x32_bf16 v[32:35], v[156:159], v[204:207], v[32:35]
	s_setprio 0
	s_barrier
; #define PG8_STAGE(bufoff, gbase, voff) do { _Pragma("unroll") for (int _i = 0; _i < 2; ++_i) \
;         __builtin_amdgcn_global_load_lds((const unsigned*)((const char*)(gbase) + (voff)[_i]), (LAS unsigned*)(lds + (bufoff) + ldsw + _i * 8192), 16, 0, 0); } while (0)
; #define PG8_LDA(dst, b, h) do { _Pragma("unroll") for (int m = 0; m < 4; ++m) _Pragma("unroll") for (int k = 0; k < 2; ++k) dst[m][k] = *(const LAS bf16x8*)(lds + PG8_SA(b, h) + aoff + m * 2048 + k * 1024); } while (0)
; #define PG8_MMA(ai, bj, At, Bt) do { __builtin_amdgcn_s_setprio(1); _Pragma("unroll") for (int m = 0; m < 4; ++m) _Pragma("unroll") for (int n = 0; n < 2; ++n) _Pragma("unroll") for (int k = 0; k < 2; ++k) \
;         acc[ai][bj][m][n] = __builtin_amdgcn_mfma_f32_16x16x32_bf16(Bt[n][k], At[m][k], acc[ai][bj][m][n], 0, 0, 0); __builtin_amdgcn_s_setprio(0); } while (0)
; #define PG8_WAIT_V(n) asm volatile("s_waitcnt vmcnt(" #n ")" ::: "memory")
; #define PG8_WAIT_L(n) asm volatile("s_waitcnt lgkmcnt(" #n ")" ::: "memory")
; #define PG8_BAR __builtin_amdgcn_s_barrier()
; #define PG8_SCHED __builtin_amdgcn_sched_barrier(0)
; template <class Epi, class Sched>
; __device__ __forceinline__ void gemm_phase(LAS unsigned char* lds, const GemmP g, const Sched& S, const Epi& E, int tid) {
;     ...
;             PG8_LDA(At, 1, 1); PG8_STAGE(PG8_SB(1, 0), b3, voffB); PG8_STAGE(PG8_SB(1, 1), b3 + hstepB, voffB); PG8_STAGE(PG8_SA(1, 0), a3, voffA);
;             PG8_WAIT_V(8); PG8_WAIT_L(0); PG8_BAR; PG8_MMA(1, 0, At, B0); PG8_MMA(1, 1, At, B1); PG8_BAR; PG8_SCHED;
;         }
;         if (wr == 0) PG8_BAR;
	s_add_i32 s8, s15, s74
	v_lshl_add_u64 v[212:213], v[212:213], 0, s[46:47]
	s_mov_b32 m0, s8
	ds_read_b128 v[160:163], v211 offset:49152
	ds_read_b128 v[164:167], v211 offset:50176
	ds_read_b128 v[168:171], v211 offset:51200
	ds_read_b128 v[172:175], v211 offset:52224
	ds_read_b128 v[176:179], v211 offset:53248
	ds_read_b128 v[180:183], v211 offset:54272
	ds_read_b128 v[184:187], v211 offset:55296
	ds_read_b128 v[204:207], v211 offset:56320
	global_load_lds_dwordx4 v[212:213], off
	s_add_i32 m0, s8, 0x2000
	s_add_u32 s6, s6, 0x40080
	v_lshl_add_u64 v[212:213], v[214:215], 0, s[46:47]
	s_addc_u32 s7, s7, 0
	s_add_i32 s8, s16, s74
	global_load_lds_dwordx4 v[212:213], off
	v_lshl_add_u64 v[212:213], s[6:7], 0, v[190:191]
	s_mov_b32 m0, s8
	s_nop 0
	global_load_lds_dwordx4 v[212:213], off
	v_lshl_add_u64 v[212:213], s[6:7], 0, v[194:195]
	s_add_i32 m0, s8, 0x2000
	s_nop 0
	global_load_lds_dwordx4 v[212:213], off
	v_lshl_add_u64 v[212:213], v[216:217], 0, s[46:47]
	s_mov_b32 m0, s82
	s_nop 0
	global_load_lds_dwordx4 v[212:213], off
	v_lshl_add_u64 v[212:213], v[218:219], 0, s[46:47]
	s_mov_b32 m0, s83
	s_nop 0
	global_load_lds_dwordx4 v[212:213], off
	s_waitcnt vmcnt(8)
	s_waitcnt lgkmcnt(0)
	s_barrier
	s_setprio 1
	s_waitcnt lgkmcnt(0)
	v_mfma_f32_16x16x32_bf16 v[92:95], v[128:131], v[160:163], v[92:95]
	v_mfma_f32_16x16x32_bf16 v[88:91], v[136:139], v[160:163], v[88:91]
	v_mfma_f32_16x16x32_bf16 v[84:87], v[128:131], v[168:171], v[84:87]
	v_mfma_f32_16x16x32_bf16 v[80:83], v[136:139], v[168:171], v[80:83]
	v_mfma_f32_16x16x32_bf16 v[76:79], v[128:131], v[176:179], v[76:79]
	v_mfma_f32_16x16x32_bf16 v[72:75], v[136:139], v[176:179], v[72:75]
	v_mfma_f32_16x16x32_bf16 v[64:67], v[128:131], v[184:187], v[64:67]
	v_mfma_f32_16x16x32_bf16 v[56:59], v[136:139], v[184:187], v[56:59]
	v_mfma_f32_16x16x32_bf16 v[92:95], v[132:135], v[164:167], v[92:95]
	v_mfma_f32_16x16x32_bf16 v[88:91], v[140:143], v[164:167], v[88:91]
	v_mfma_f32_16x16x32_bf16 v[84:87], v[132:135], v[172:175], v[84:87]
	v_mfma_f32_16x16x32_bf16 v[80:83], v[140:143], v[172:175], v[80:83]
	v_mfma_f32_16x16x32_bf16 v[76:79], v[132:135], v[180:183], v[76:79]
	v_mfma_f32_16x16x32_bf16 v[72:75], v[140:143], v[180:183], v[72:75]
	v_mfma_f32_16x16x32_bf16 v[64:67], v[132:135], v[204:207], v[64:67]
	v_mfma_f32_16x16x32_bf16 v[56:59], v[140:143], v[204:207], v[56:59]
	s_setprio 0
	s_setprio 1
	v_mfma_f32_16x16x32_bf16 v[28:31], v[144:147], v[160:163], v[28:31]
	v_mfma_f32_16x16x32_bf16 v[24:27], v[152:155], v[160:163], v[24:27]
	v_mfma_f32_16x16x32_bf16 v[20:23], v[144:147], v[168:171], v[20:23]
	v_mfma_f32_16x16x32_bf16 v[16:19], v[152:155], v[168:171], v[16:19]
	v_mfma_f32_16x16x32_bf16 v[12:15], v[144:147], v[176:179], v[12:15]
	v_mfma_f32_16x16x32_bf16 v[8:11], v[152:155], v[176:179], v[8:11]
	v_mfma_f32_16x16x32_bf16 v[4:7], v[144:147], v[184:187], v[4:7]
	v_mfma_f32_16x16x32_bf16 v[0:3], v[152:155], v[184:187], v[0:3]
	v_mfma_f32_16x16x32_bf16 v[28:31], v[148:151], v[164:167], v[28:31]
	v_mfma_f32_16x16x32_bf16 v[24:27], v[156:159], v[164:167], v[24:27]
	v_mfma_f32_16x16x32_bf16 v[20:23], v[148:151], v[172:175], v[20:23]
	v_mfma_f32_16x16x32_bf16 v[16:19], v[156:159], v[172:175], v[16:19]
	v_mfma_f32_16x16x32_bf16 v[12:15], v[148:151], v[180:183], v[12:15]
	v_mfma_f32_16x16x32_bf16 v[8:11], v[156:159], v[180:183], v[8:11]
	v_mfma_f32_16x16x32_bf16 v[4:7], v[148:151], v[204:207], v[4:7]
	v_mfma_f32_16x16x32_bf16 v[0:3], v[156:159], v[204:207], v[0:3]
	s_setprio 0
	s_barrier
	s_add_i32 s14, s14, 2
	s_add_u32 s12, s12, 0x100
	s_addc_u32 s13, s13, 0
	s_add_u32 s4, s4, 0x100
	s_addc_u32 s5, s5, 0
	s_cmp_gt_u32 s14, 13
	s_cbranch_scc0 .LBB0_445
	s_and_b64 vcc, exec, s[48:49]
	s_cbranch_vccz .LBB0_448
	s_barrier

; #define PG8_STAGE(bufoff, gbase, voff) do { _Pragma("unroll") for (int _i = 0; _i < 2; ++_i) \
;         __builtin_amdgcn_global_load_lds((const unsigned*)((const char*)(gbase) + (voff)[_i]), (LAS unsigned*)(lds + (bufoff) + ldsw + _i * 8192), 16, 0, 0); } while (0)
; #define PG8_LDA(dst, b, h) do { _Pragma("unroll") for (int m = 0; m < 4; ++m) _Pragma("unroll") for (int k = 0; k < 2; ++k) dst[m][k] = *(const LAS bf16x8*)(lds + PG8_SA(b, h) + aoff + m * 2048 + k * 1024); } while (0)
; #define PG8_LDB(dst, b, h) do { _Pragma("unroll") for (int n = 0; n < 2; ++n) _Pragma("unroll") for (int k = 0; k < 2; ++k) dst[n][k] = *(const LAS bf16x8*)(lds + PG8_SB(b, h) + boff + n * 2048 + k * 1024); } while (0)
; #define PG8_MMA(ai, bj, At, Bt) do { __builtin_amdgcn_s_setprio(1); _Pragma("unroll") for (int m = 0; m < 4; ++m) _Pragma("unroll") for (int n = 0; n < 2; ++n) _Pragma("unroll") for (int k = 0; k < 2; ++k) \
;         acc[ai][bj][m][n] = __builtin_amdgcn_mfma_f32_16x16x32_bf16(Bt[n][k], At[m][k], acc[ai][bj][m][n], 0, 0, 0); __builtin_amdgcn_s_setprio(0); } while (0)
; #define PG8_WAIT_V(n) asm volatile("s_waitcnt vmcnt(" #n ")" ::: "memory")
; #define PG8_WAIT_L(n) asm volatile("s_waitcnt lgkmcnt(" #n ")" ::: "memory")
; #define PG8_BAR __builtin_amdgcn_s_barrier()
; #define PG8_SCHED __builtin_amdgcn_sched_barrier(0)
; template <class Epi, class Sched>
; __device__ __forceinline__ void gemm_phase(LAS unsigned char* lds, const GemmP g, const Sched& S, const Epi& E, int tid) {
;     ...
;         for (int t = 0; t < nt; t += 2) {
;             const bool last = (t == nt - 2);
;             const char* a1 = cA + (size_t)(t + 1) * kstep;
;             const char* a2 = last ? nA : cA + (size_t)(t + 2) * kstep; const char* b2 = last ? nB : cB + (size_t)(t + 2) * kstep;
;             const char* a3 = a2 + kstep; const char* b3 = b2 + kstep;
;             PG8_LDB(B0, 0, 0); PG8_LDB(B1, 0, 1); PG8_SCHED; PG8_LDA(At, 0, 0); PG8_STAGE(PG8_SA(1, 1), a1 + hstepA, voffA);
;             PG8_WAIT_V(8); PG8_WAIT_L(0); PG8_BAR; PG8_MMA(0, 0, At, B0); PG8_MMA(0, 1, At, B1); PG8_BAR; PG8_SCHED;
;             PG8_LDA(At, 0, 1); PG8_STAGE(PG8_SB(0, 0), b2, voffB); PG8_STAGE(PG8_SB(0, 1), b2 + hstepB, voffB); PG8_STAGE(PG8_SA(0, 0), a2, voffA);
.LBB0_996:
	s_add_u32 s28, s26, 0xfffc0080
	s_addc_u32 s29, s27, -1
	s_add_i32 s60, 0, 0x10000
	s_cmp_eq_u32 s57, 12
	s_cselect_b32 s31, s23, s29
	s_cselect_b32 s30, s22, s28
	s_cselect_b32 s29, s25, s56
	s_cselect_b32 s28, s24, s5
	s_add_i32 s62, 0, 0x14000
	v_add_u32_e32 v152, s60, v166
	v_add_u32_e32 v164, s62, v166
	ds_read_b128 v[140:143], v152
	ds_read_b128 v[144:147], v152 offset:1024
	ds_read_b128 v[148:151], v152 offset:2048
	ds_read_b128 v[152:155], v152 offset:3072
	ds_read_b128 v[156:159], v164
	ds_read_b128 v[160:163], v164 offset:1024
	ds_read_b128 v[168:171], v164 offset:2048
	ds_read_b128 v[172:175], v164 offset:3072
	v_lshl_add_u64 v[164:165], s[26:27], 0, v[138:139]
	s_add_i32 m0, s42, 0xc000
	ds_read_b128 v[176:179], v167
	ds_read_b128 v[180:183], v167 offset:1024
	ds_read_b128 v[184:187], v167 offset:2048
	ds_read_b128 v[188:191], v167 offset:3072
	ds_read_b128 v[192:195], v167 offset:4096
	ds_read_b128 v[206:209], v167 offset:5120
	ds_read_b128 v[210:213], v167 offset:6144
	ds_read_b128 v[214:217], v167 offset:7168
	global_load_lds_dwordx4 v[164:165], off
	v_lshl_add_u64 v[164:165], s[26:27], 0, v[136:137]
	s_add_i32 m0, s42, 0xe000
	s_nop 0
	global_load_lds_dwordx4 v[164:165], off
	s_cmp_eq_u32 s57, -2
	s_cbranch_scc1 .Lfirstit_3
	s_waitcnt vmcnt(8)
.Lfirstit_3:
	s_waitcnt lgkmcnt(0)
	s_barrier
	s_setprio 1
	s_waitcnt lgkmcnt(0)
	v_mfma_f32_16x16x32_bf16 v[124:127], v[140:143], v[176:179], v[124:127]
	v_mfma_f32_16x16x32_bf16 v[120:123], v[148:151], v[176:179], v[120:123]
	v_mfma_f32_16x16x32_bf16 v[108:111], v[140:143], v[184:187], v[108:111]
	v_mfma_f32_16x16x32_bf16 v[104:107], v[148:151], v[184:187], v[104:107]
	v_mfma_f32_16x16x32_bf16 v[92:95], v[140:143], v[192:195], v[92:95]
	v_mfma_f32_16x16x32_bf16 v[88:91], v[148:151], v[192:195], v[88:91]
	v_mfma_f32_16x16x32_bf16 v[76:79], v[140:143], v[210:213], v[76:79]
	v_mfma_f32_16x16x32_bf16 v[72:75], v[148:151], v[210:213], v[72:75]
	v_mfma_f32_16x16x32_bf16 v[124:127], v[144:147], v[180:183], v[124:127]
	v_mfma_f32_16x16x32_bf16 v[120:123], v[152:155], v[180:183], v[120:123]
	v_mfma_f32_16x16x32_bf16 v[108:111], v[144:147], v[188:191], v[108:111]
	v_mfma_f32_16x16x32_bf16 v[104:107], v[152:155], v[188:191], v[104:107]
	v_mfma_f32_16x16x32_bf16 v[92:95], v[144:147], v[206:209], v[92:95]
	v_mfma_f32_16x16x32_bf16 v[88:91], v[152:155], v[206:209], v[88:91]
	v_mfma_f32_16x16x32_bf16 v[76:79], v[144:147], v[214:217], v[76:79]
	v_mfma_f32_16x16x32_bf16 v[72:75], v[152:155], v[214:217], v[72:75]
	s_setprio 0
	s_setprio 1
	v_mfma_f32_16x16x32_bf16 v[116:119], v[156:159], v[176:179], v[116:119]
	v_mfma_f32_16x16x32_bf16 v[112:115], v[168:171], v[176:179], v[112:115]
	v_mfma_f32_16x16x32_bf16 v[100:103], v[156:159], v[184:187], v[100:103]
	v_mfma_f32_16x16x32_bf16 v[96:99], v[168:171], v[184:187], v[96:99]
	v_mfma_f32_16x16x32_bf16 v[84:87], v[156:159], v[192:195], v[84:87]
	v_mfma_f32_16x16x32_bf16 v[80:83], v[168:171], v[192:195], v[80:83]
	v_mfma_f32_16x16x32_bf16 v[68:71], v[156:159], v[210:213], v[68:71]
	v_mfma_f32_16x16x32_bf16 v[64:67], v[168:171], v[210:213], v[64:67]
	v_mfma_f32_16x16x32_bf16 v[116:119], v[160:163], v[180:183], v[116:119]
	v_mfma_f32_16x16x32_bf16 v[112:115], v[172:175], v[180:183], v[112:115]
	v_mfma_f32_16x16x32_bf16 v[100:103], v[160:163], v[188:191], v[100:103]
	v_mfma_f32_16x16x32_bf16 v[96:99], v[172:175], v[188:191], v[96:99]
	v_mfma_f32_16x16x32_bf16 v[84:87], v[160:163], v[206:209], v[84:87]
	v_mfma_f32_16x16x32_bf16 v[80:83], v[172:175], v[206:209], v[80:83]
	v_mfma_f32_16x16x32_bf16 v[68:71], v[160:163], v[214:217], v[68:71]
	v_mfma_f32_16x16x32_bf16 v[64:67], v[172:175], v[214:217], v[64:67]
	s_setprio 0
	s_barrier
	s_add_i32 s60, s60, s41
	v_lshl_add_u64 v[164:165], s[28:29], 0, v[130:131]
	s_mov_b32 m0, s60
	ds_read_b128 v[176:179], v167 offset:16384
	ds_read_b128 v[180:183], v167 offset:17408
	ds_read_b128 v[184:187], v167 offset:18432
	ds_read_b128 v[188:191], v167 offset:19456
	ds_read_b128 v[192:195], v167 offset:20480
	ds_read_b128 v[206:209], v167 offset:21504
	ds_read_b128 v[210:213], v167 offset:22528
	ds_read_b128 v[214:217], v167 offset:23552
	global_load_lds_dwordx4 v[164:165], off
	s_add_i32 m0, s60, 0x2000
	s_add_u32 s60, s28, 0x40000
	v_lshl_add_u64 v[198:199], s[28:29], 0, v[134:135]
	s_addc_u32 s61, s29, 0
	s_add_i32 s62, s62, s41
	global_load_lds_dwordx4 v[198:199], off
	v_lshl_add_u64 v[200:201], s[60:61], 0, v[130:131]
	s_mov_b32 m0, s62
	v_lshl_add_u64 v[220:221], s[30:31], 0, v[132:133]
	global_load_lds_dwordx4 v[200:201], off
	v_lshl_add_u64 v[200:201], s[60:61], 0, v[134:135]
	s_add_i32 m0, s62, 0x2000
	s_nop 0
	global_load_lds_dwordx4 v[200:201], off
	v_lshl_add_u64 v[200:201], s[30:31], 0, v[128:129]
	s_mov_b32 m0, s42
	s_nop 0
	global_load_lds_dwordx4 v[200:201], off
	s_mov_b32 m0, s45
	s_nop 0
	global_load_lds_dwordx4 v[220:221], off
	s_waitcnt vmcnt(8)
	s_waitcnt lgkmcnt(0)
	s_barrier
; #define PG8_STAGE(bufoff, gbase, voff) do { _Pragma("unroll") for (int _i = 0; _i < 2; ++_i) \
;         __builtin_amdgcn_global_load_lds((const unsigned*)((const char*)(gbase) + (voff)[_i]), (LAS unsigned*)(lds + (bufoff) + ldsw + _i * 8192), 16, 0, 0); } while (0)
; #define PG8_LDA(dst, b, h) do { _Pragma("unroll") for (int m = 0; m < 4; ++m) _Pragma("unroll") for (int k = 0; k < 2; ++k) dst[m][k] = *(const LAS bf16x8*)(lds + PG8_SA(b, h) + aoff + m * 2048 + k * 1024); } while (0)
; #define PG8_LDB(dst, b, h) do { _Pragma("unroll") for (int n = 0; n < 2; ++n) _Pragma("unroll") for (int k = 0; k < 2; ++k) dst[n][k] = *(const LAS bf16x8*)(lds + PG8_SB(b, h) + boff + n * 2048 + k * 1024); } while (0)
; #define PG8_MMA(ai, bj, At, Bt) do { __builtin_amdgcn_s_setprio(1); _Pragma("unroll") for (int m = 0; m < 4; ++m) _Pragma("unroll") for (int n = 0; n < 2; ++n) _Pragma("unroll") for (int k = 0; k < 2; ++k) \
;         acc[ai][bj][m][n] = __builtin_amdgcn_mfma_f32_16x16x32_bf16(Bt[n][k], At[m][k], acc[ai][bj][m][n], 0, 0, 0); __builtin_amdgcn_s_setprio(0); } while (0)
; #define PG8_WAIT_V(n) asm volatile("s_waitcnt vmcnt(" #n ")" ::: "memory")
; #define PG8_WAIT_L(n) asm volatile("s_waitcnt lgkmcnt(" #n ")" ::: "memory")
; #define PG8_BAR __builtin_amdgcn_s_barrier()
; #define PG8_SCHED __builtin_amdgcn_sched_barrier(0)
; template <class Epi, class Sched>
; __device__ __forceinline__ void gemm_phase(LAS unsigned char* lds, const GemmP g, const Sched& S, const Epi& E, int tid) {
;     ...
;             PG8_WAIT_V(8); PG8_WAIT_L(0); PG8_BAR; PG8_MMA(1, 0, At, B0); PG8_MMA(1, 1, At, B1); PG8_BAR; PG8_SCHED;
;             PG8_LDB(B0, 1, 0); PG8_LDB(B1, 1, 1); PG8_SCHED; PG8_LDA(At, 1, 0); PG8_STAGE(PG8_SA(0, 1), a2 + hstepA, voffA);
;             PG8_WAIT_V(8); PG8_WAIT_L(0); PG8_BAR; PG8_MMA(0, 0, At, B0); PG8_MMA(0, 1, At, B1); PG8_BAR; PG8_SCHED;
	s_setprio 1
	s_waitcnt lgkmcnt(0)
	v_mfma_f32_16x16x32_bf16 v[60:63], v[140:143], v[176:179], v[60:63]
	v_mfma_f32_16x16x32_bf16 v[56:59], v[148:151], v[176:179], v[56:59]
	v_mfma_f32_16x16x32_bf16 v[44:47], v[140:143], v[184:187], v[44:47]
	v_mfma_f32_16x16x32_bf16 v[40:43], v[148:151], v[184:187], v[40:43]
	v_mfma_f32_16x16x32_bf16 v[28:31], v[140:143], v[192:195], v[28:31]
	v_mfma_f32_16x16x32_bf16 v[24:27], v[148:151], v[192:195], v[24:27]
	v_mfma_f32_16x16x32_bf16 v[12:15], v[140:143], v[210:213], v[12:15]
	v_mfma_f32_16x16x32_bf16 v[8:11], v[148:151], v[210:213], v[8:11]
	v_mfma_f32_16x16x32_bf16 v[60:63], v[144:147], v[180:183], v[60:63]
	v_mfma_f32_16x16x32_bf16 v[56:59], v[152:155], v[180:183], v[56:59]
	v_mfma_f32_16x16x32_bf16 v[44:47], v[144:147], v[188:191], v[44:47]
	v_mfma_f32_16x16x32_bf16 v[40:43], v[152:155], v[188:191], v[40:43]
	v_mfma_f32_16x16x32_bf16 v[28:31], v[144:147], v[206:209], v[28:31]
	v_mfma_f32_16x16x32_bf16 v[24:27], v[152:155], v[206:209], v[24:27]
	v_mfma_f32_16x16x32_bf16 v[12:15], v[144:147], v[214:217], v[12:15]
	v_mfma_f32_16x16x32_bf16 v[8:11], v[152:155], v[214:217], v[8:11]
	s_setprio 0
	s_setprio 1
	v_mfma_f32_16x16x32_bf16 v[52:55], v[156:159], v[176:179], v[52:55]
	v_mfma_f32_16x16x32_bf16 v[48:51], v[168:171], v[176:179], v[48:51]
	v_mfma_f32_16x16x32_bf16 v[36:39], v[156:159], v[184:187], v[36:39]
	v_mfma_f32_16x16x32_bf16 v[32:35], v[168:171], v[184:187], v[32:35]
	v_mfma_f32_16x16x32_bf16 v[20:23], v[156:159], v[192:195], v[20:23]
	v_mfma_f32_16x16x32_bf16 v[16:19], v[168:171], v[192:195], v[16:19]
	v_mfma_f32_16x16x32_bf16 v[4:7], v[156:159], v[210:213], v[4:7]
	v_mfma_f32_16x16x32_bf16 v[0:3], v[168:171], v[210:213], v[0:3]
	v_mfma_f32_16x16x32_bf16 v[52:55], v[160:163], v[180:183], v[52:55]
	v_mfma_f32_16x16x32_bf16 v[48:51], v[172:175], v[180:183], v[48:51]
	v_mfma_f32_16x16x32_bf16 v[36:39], v[160:163], v[188:191], v[36:39]
	v_mfma_f32_16x16x32_bf16 v[32:35], v[172:175], v[188:191], v[32:35]
	v_mfma_f32_16x16x32_bf16 v[20:23], v[160:163], v[206:209], v[20:23]
	v_mfma_f32_16x16x32_bf16 v[16:19], v[172:175], v[206:209], v[16:19]
	v_mfma_f32_16x16x32_bf16 v[4:7], v[160:163], v[214:217], v[4:7]
	v_mfma_f32_16x16x32_bf16 v[0:3], v[172:175], v[214:217], v[0:3]
	s_setprio 0
	s_barrier
	s_add_i32 s60, 0, 0x18000
	s_add_i32 s61, 0, 0x1c000
	v_add_u32_e32 v152, s60, v166
	v_add_u32_e32 v172, s61, v166
	ds_read_b128 v[140:143], v152
	ds_read_b128 v[144:147], v152 offset:1024
	ds_read_b128 v[148:151], v152 offset:2048
	ds_read_b128 v[152:155], v152 offset:3072
	ds_read_b128 v[156:159], v172
	ds_read_b128 v[160:163], v172 offset:1024
	ds_read_b128 v[168:171], v172 offset:2048
	ds_read_b128 v[172:175], v172 offset:3072
	s_add_u32 s30, s30, 0x40000
	s_addc_u32 s31, s31, 0
	s_mov_b32 m0, s46
	v_lshl_add_u64 v[222:223], s[30:31], 0, v[128:129]
	ds_read_b128 v[176:179], v167 offset:32768
	ds_read_b128 v[180:183], v167 offset:33792
	ds_read_b128 v[184:187], v167 offset:34816
	ds_read_b128 v[188:191], v167 offset:35840
	ds_read_b128 v[192:195], v167 offset:36864
	ds_read_b128 v[206:209], v167 offset:37888
	ds_read_b128 v[210:213], v167 offset:38912
	ds_read_b128 v[214:217], v167 offset:39936
	global_load_lds_dwordx4 v[222:223], off
	v_lshl_add_u64 v[222:223], s[30:31], 0, v[132:133]
	s_mov_b32 m0, s47
	s_nop 0
	global_load_lds_dwordx4 v[222:223], off
	s_waitcnt vmcnt(8)
	s_waitcnt lgkmcnt(0)
	s_barrier
	s_setprio 1
	s_waitcnt lgkmcnt(0)
	v_mfma_f32_16x16x32_bf16 v[124:127], v[140:143], v[176:179], v[124:127]
	v_mfma_f32_16x16x32_bf16 v[120:123], v[148:151], v[176:179], v[120:123]
	v_mfma_f32_16x16x32_bf16 v[108:111], v[140:143], v[184:187], v[108:111]
	v_mfma_f32_16x16x32_bf16 v[104:107], v[148:151], v[184:187], v[104:107]
	v_mfma_f32_16x16x32_bf16 v[92:95], v[140:143], v[192:195], v[92:95]
	v_mfma_f32_16x16x32_bf16 v[88:91], v[148:151], v[192:195], v[88:91]
	v_mfma_f32_16x16x32_bf16 v[76:79], v[140:143], v[210:213], v[76:79]
	v_mfma_f32_16x16x32_bf16 v[72:75], v[148:151], v[210:213], v[72:75]
	v_mfma_f32_16x16x32_bf16 v[124:127], v[144:147], v[180:183], v[124:127]
	v_mfma_f32_16x16x32_bf16 v[120:123], v[152:155], v[180:183], v[120:123]
	v_mfma_f32_16x16x32_bf16 v[108:111], v[144:147], v[188:191], v[108:111]
	v_mfma_f32_16x16x32_bf16 v[104:107], v[152:155], v[188:191], v[104:107]
	v_mfma_f32_16x16x32_bf16 v[92:95], v[144:147], v[206:209], v[92:95]
	v_mfma_f32_16x16x32_bf16 v[88:91], v[152:155], v[206:209], v[88:91]
	v_mfma_f32_16x16x32_bf16 v[76:79], v[144:147], v[214:217], v[76:79]
	v_mfma_f32_16x16x32_bf16 v[72:75], v[152:155], v[214:217], v[72:75]
	s_setprio 0
	s_setprio 1
	v_mfma_f32_16x16x32_bf16 v[116:119], v[156:159], v[176:179], v[116:119]
	v_mfma_f32_16x16x32_bf16 v[112:115], v[168:171], v[176:179], v[112:115]
	v_mfma_f32_16x16x32_bf16 v[100:103], v[156:159], v[184:187], v[100:103]
	v_mfma_f32_16x16x32_bf16 v[96:99], v[168:171], v[184:187], v[96:99]
	v_mfma_f32_16x16x32_bf16 v[84:87], v[156:159], v[192:195], v[84:87]
	v_mfma_f32_16x16x32_bf16 v[80:83], v[168:171], v[192:195], v[80:83]
	v_mfma_f32_16x16x32_bf16 v[68:71], v[156:159], v[210:213], v[68:71]
	v_mfma_f32_16x16x32_bf16 v[64:67], v[168:171], v[210:213], v[64:67]
	v_mfma_f32_16x16x32_bf16 v[116:119], v[160:163], v[180:183], v[116:119]
	v_mfma_f32_16x16x32_bf16 v[112:115], v[172:175], v[180:183], v[112:115]
	v_mfma_f32_16x16x32_bf16 v[100:103], v[160:163], v[188:191], v[100:103]
	v_mfma_f32_16x16x32_bf16 v[96:99], v[172:175], v[188:191], v[96:99]
	v_mfma_f32_16x16x32_bf16 v[84:87], v[160:163], v[206:209], v[84:87]
	v_mfma_f32_16x16x32_bf16 v[80:83], v[172:175], v[206:209], v[80:83]
	v_mfma_f32_16x16x32_bf16 v[68:71], v[160:163], v[214:217], v[68:71]
	v_mfma_f32_16x16x32_bf16 v[64:67], v[172:175], v[214:217], v[64:67]
	s_setprio 0
	s_barrier
; #define PG8_STAGE(bufoff, gbase, voff) do { _Pragma("unroll") for (int _i = 0; _i < 2; ++_i) \
;         __builtin_amdgcn_global_load_lds((const unsigned*)((const char*)(gbase) + (voff)[_i]), (LAS unsigned*)(lds + (bufoff) + ldsw + _i * 8192), 16, 0, 0); } while (0)
; #define PG8_LDA(dst, b, h) do { _Pragma("unroll") for (int m = 0; m < 4; ++m) _Pragma("unroll") for (int k = 0; k < 2; ++k) dst[m][k] = *(const LAS bf16x8*)(lds + PG8_SA(b, h) + aoff + m * 2048 + k * 1024); } while (0)
; #define PG8_MMA(ai, bj, At, Bt) do { __builtin_amdgcn_s_setprio(1); _Pragma("unroll") for (int m = 0; m < 4; ++m) _Pragma("unroll") for (int n = 0; n < 2; ++n) _Pragma("unroll") for (int k = 0; k < 2; ++k) \
;         acc[ai][bj][m][n] = __builtin_amdgcn_mfma_f32_16x16x32_bf16(Bt[n][k], At[m][k], acc[ai][bj][m][n], 0, 0, 0); __builtin_amdgcn_s_setprio(0); } while (0)
; #define PG8_WAIT_V(n) asm volatile("s_waitcnt vmcnt(" #n ")" ::: "memory")
; #define PG8_WAIT_L(n) asm volatile("s_waitcnt lgkmcnt(" #n ")" ::: "memory")
; #define PG8_BAR __builtin_amdgcn_s_barrier()
; #define PG8_SCHED __builtin_amdgcn_sched_barrier(0)
; template <class Epi, class Sched>
; __device__ __forceinline__ void gemm_phase(LAS unsigned char* lds, const GemmP g, const Sched& S, const Epi& E, int tid) {
;     ...
;             PG8_LDA(At, 1, 1); PG8_STAGE(PG8_SB(1, 0), b3, voffB); PG8_STAGE(PG8_SB(1, 1), b3 + hstepB, voffB); PG8_STAGE(PG8_SA(1, 0), a3, voffA);
;             PG8_WAIT_V(8); PG8_WAIT_L(0); PG8_BAR; PG8_MMA(1, 0, At, B0); PG8_MMA(1, 1, At, B1); PG8_BAR; PG8_SCHED;
;         }
;         if (wr == 0) PG8_BAR;
	s_add_i32 s30, s60, s41
	v_lshl_add_u64 v[164:165], v[164:165], 0, s[80:81]
	s_mov_b32 m0, s30
	ds_read_b128 v[176:179], v167 offset:49152
	ds_read_b128 v[180:183], v167 offset:50176
	ds_read_b128 v[184:187], v167 offset:51200
	ds_read_b128 v[188:191], v167 offset:52224
	ds_read_b128 v[192:195], v167 offset:53248
	ds_read_b128 v[206:209], v167 offset:54272
	ds_read_b128 v[210:213], v167 offset:55296
	ds_read_b128 v[214:217], v167 offset:56320
	global_load_lds_dwordx4 v[164:165], off
	s_add_i32 m0, s30, 0x2000
	s_add_u32 s28, s28, 0x40080
	v_lshl_add_u64 v[164:165], v[198:199], 0, s[80:81]
	s_addc_u32 s29, s29, 0
	s_add_i32 s30, s61, s41
	global_load_lds_dwordx4 v[164:165], off
	v_lshl_add_u64 v[164:165], s[28:29], 0, v[130:131]
	s_mov_b32 m0, s30
	s_nop 0
	global_load_lds_dwordx4 v[164:165], off
	v_lshl_add_u64 v[164:165], s[28:29], 0, v[134:135]
	s_add_i32 m0, s30, 0x2000
	s_nop 0
	global_load_lds_dwordx4 v[164:165], off
	v_lshl_add_u64 v[164:165], v[200:201], 0, s[80:81]
	s_mov_b32 m0, s51
	s_nop 0
	global_load_lds_dwordx4 v[164:165], off
	v_lshl_add_u64 v[164:165], v[220:221], 0, s[80:81]
	s_mov_b32 m0, s52
	s_nop 0
	global_load_lds_dwordx4 v[164:165], off
	s_waitcnt vmcnt(8)
	s_waitcnt lgkmcnt(0)
	s_barrier
	s_setprio 1
	s_waitcnt lgkmcnt(0)
	v_mfma_f32_16x16x32_bf16 v[60:63], v[140:143], v[176:179], v[60:63]
	v_mfma_f32_16x16x32_bf16 v[56:59], v[148:151], v[176:179], v[56:59]
	v_mfma_f32_16x16x32_bf16 v[44:47], v[140:143], v[184:187], v[44:47]
	v_mfma_f32_16x16x32_bf16 v[40:43], v[148:151], v[184:187], v[40:43]
	v_mfma_f32_16x16x32_bf16 v[28:31], v[140:143], v[192:195], v[28:31]
	v_mfma_f32_16x16x32_bf16 v[24:27], v[148:151], v[192:195], v[24:27]
	v_mfma_f32_16x16x32_bf16 v[12:15], v[140:143], v[210:213], v[12:15]
	v_mfma_f32_16x16x32_bf16 v[8:11], v[148:151], v[210:213], v[8:11]
	v_mfma_f32_16x16x32_bf16 v[60:63], v[144:147], v[180:183], v[60:63]
	v_mfma_f32_16x16x32_bf16 v[56:59], v[152:155], v[180:183], v[56:59]
	v_mfma_f32_16x16x32_bf16 v[44:47], v[144:147], v[188:191], v[44:47]
	v_mfma_f32_16x16x32_bf16 v[40:43], v[152:155], v[188:191], v[40:43]
	v_mfma_f32_16x16x32_bf16 v[28:31], v[144:147], v[206:209], v[28:31]
	v_mfma_f32_16x16x32_bf16 v[24:27], v[152:155], v[206:209], v[24:27]
	v_mfma_f32_16x16x32_bf16 v[12:15], v[144:147], v[214:217], v[12:15]
	v_mfma_f32_16x16x32_bf16 v[8:11], v[152:155], v[214:217], v[8:11]
	s_setprio 0
	s_setprio 1
	v_mfma_f32_16x16x32_bf16 v[52:55], v[156:159], v[176:179], v[52:55]
	v_mfma_f32_16x16x32_bf16 v[48:51], v[168:171], v[176:179], v[48:51]
	v_mfma_f32_16x16x32_bf16 v[36:39], v[156:159], v[184:187], v[36:39]
	v_mfma_f32_16x16x32_bf16 v[32:35], v[168:171], v[184:187], v[32:35]
	v_mfma_f32_16x16x32_bf16 v[20:23], v[156:159], v[192:195], v[20:23]
	v_mfma_f32_16x16x32_bf16 v[16:19], v[168:171], v[192:195], v[16:19]
	v_mfma_f32_16x16x32_bf16 v[4:7], v[156:159], v[210:213], v[4:7]
	v_mfma_f32_16x16x32_bf16 v[0:3], v[168:171], v[210:213], v[0:3]
	v_mfma_f32_16x16x32_bf16 v[52:55], v[160:163], v[180:183], v[52:55]
	v_mfma_f32_16x16x32_bf16 v[48:51], v[172:175], v[180:183], v[48:51]
	v_mfma_f32_16x16x32_bf16 v[36:39], v[160:163], v[188:191], v[36:39]
	v_mfma_f32_16x16x32_bf16 v[32:35], v[172:175], v[188:191], v[32:35]
	v_mfma_f32_16x16x32_bf16 v[20:23], v[160:163], v[206:209], v[20:23]
	v_mfma_f32_16x16x32_bf16 v[16:19], v[172:175], v[206:209], v[16:19]
	v_mfma_f32_16x16x32_bf16 v[4:7], v[160:163], v[214:217], v[4:7]
	v_mfma_f32_16x16x32_bf16 v[0:3], v[172:175], v[214:217], v[0:3]
	s_setprio 0
	s_barrier
	s_add_i32 s57, s57, 2
	s_add_u32 s5, s5, 0x100
	s_addc_u32 s56, s56, 0
	s_add_u32 s26, s26, 0x100
	s_addc_u32 s27, s27, 0
	s_cmp_gt_u32 s57, 13
	s_cbranch_scc0 .LBB0_996
	s_and_b64 vcc, exec, s[16:17]
	s_cbranch_vccz .LBB0_999
	s_barrier

; #define PG8_STAGE(bufoff, gbase, voff) do { _Pragma("unroll") for (int _i = 0; _i < 2; ++_i) \
;         __builtin_amdgcn_global_load_lds((const unsigned*)((const char*)(gbase) + (voff)[_i]), (LAS unsigned*)(lds + (bufoff) + ldsw + _i * 8192), 16, 0, 0); } while (0)
; #define PG8_LDA(dst, b, h) do { _Pragma("unroll") for (int m = 0; m < 4; ++m) _Pragma("unroll") for (int k = 0; k < 2; ++k) dst[m][k] = *(const LAS bf16x8*)(lds + PG8_SA(b, h) + aoff + m * 2048 + k * 1024); } while (0)
; #define PG8_LDB(dst, b, h) do { _Pragma("unroll") for (int n = 0; n < 2; ++n) _Pragma("unroll") for (int k = 0; k < 2; ++k) dst[n][k] = *(const LAS bf16x8*)(lds + PG8_SB(b, h) + boff + n * 2048 + k * 1024); } while (0)
; #define PG8_MMA(ai, bj, At, Bt) do { __builtin_amdgcn_s_setprio(1); _Pragma("unroll") for (int m = 0; m < 4; ++m) _Pragma("unroll") for (int n = 0; n < 2; ++n) _Pragma("unroll") for (int k = 0; k < 2; ++k) \
;         acc[ai][bj][m][n] = __builtin_amdgcn_mfma_f32_16x16x32_bf16(Bt[n][k], At[m][k], acc[ai][bj][m][n], 0, 0, 0); __builtin_amdgcn_s_setprio(0); } while (0)
; #define PG8_WAIT_V(n) asm volatile("s_waitcnt vmcnt(" #n ")" ::: "memory")
; #define PG8_WAIT_L(n) asm volatile("s_waitcnt lgkmcnt(" #n ")" ::: "memory")
; #define PG8_BAR __builtin_amdgcn_s_barrier()
; #define PG8_SCHED __builtin_amdgcn_sched_barrier(0)
; template <class Epi, class Sched>
; __device__ __forceinline__ void gemm_phase(LAS unsigned char* lds, const GemmP g, const Sched& S, const Epi& E, int tid) {
;     ...
;         for (int t = 0; t < nt; t += 2) {
;             const bool last = (t == nt - 2);
;             const char* a1 = cA + (size_t)(t + 1) * kstep;
;             const char* a2 = last ? nA : cA + (size_t)(t + 2) * kstep; const char* b2 = last ? nB : cB + (size_t)(t + 2) * kstep;
;             const char* a3 = a2 + kstep; const char* b3 = b2 + kstep;
;             PG8_LDB(B0, 0, 0); PG8_LDB(B1, 0, 1); PG8_SCHED; PG8_LDA(At, 0, 0); PG8_STAGE(PG8_SA(1, 1), a1 + hstepA, voffA);
;             PG8_WAIT_V(8); PG8_WAIT_L(0); PG8_BAR; PG8_MMA(0, 0, At, B0); PG8_MMA(0, 1, At, B1); PG8_BAR; PG8_SCHED;
;             PG8_LDA(At, 0, 1); PG8_STAGE(PG8_SB(0, 0), b2, voffB); PG8_STAGE(PG8_SB(0, 1), b2 + hstepB, voffB); PG8_STAGE(PG8_SA(0, 0), a2, voffA);
.LBB0_1163:
	s_add_u32 s8, s6, 0xfffc0080
	s_addc_u32 s9, s7, -1
	s_add_i32 s15, 0, 0x10000
	s_cmp_eq_u32 s14, 12
	s_cselect_b32 s11, s93, s9
	s_cselect_b32 s10, s92, s8
	s_cselect_b32 s9, s95, s13
	s_cselect_b32 s8, s94, s12
	s_add_i32 s18, 0, 0x14000
	v_add_u32_e32 v140, s15, v214
	v_add_u32_e32 v156, s18, v214
	ds_read_b128 v[124:127], v140
	ds_read_b128 v[132:135], v140 offset:1024
	ds_read_b128 v[136:139], v140 offset:2048
	ds_read_b128 v[140:143], v140 offset:3072
	ds_read_b128 v[144:147], v156
	ds_read_b128 v[148:151], v156 offset:1024
	ds_read_b128 v[152:155], v156 offset:2048
	ds_read_b128 v[156:159], v156 offset:3072
	v_lshl_add_u64 v[198:199], s[6:7], 0, v[208:209]
	s_add_i32 m0, s63, 0xc000
	ds_read_b128 v[160:163], v215
	ds_read_b128 v[164:167], v215 offset:1024
	ds_read_b128 v[168:171], v215 offset:2048
	ds_read_b128 v[172:175], v215 offset:3072
	ds_read_b128 v[176:179], v215 offset:4096
	ds_read_b128 v[180:183], v215 offset:5120
	ds_read_b128 v[184:187], v215 offset:6144
	ds_read_b128 v[210:213], v215 offset:7168
	global_load_lds_dwordx4 v[198:199], off
	v_lshl_add_u64 v[198:199], s[6:7], 0, v[206:207]
	s_add_i32 m0, s63, 0xe000
	s_nop 0
	global_load_lds_dwordx4 v[198:199], off
	s_cmp_eq_u32 s14, -2
	s_cbranch_scc1 .Lfirstit_4
	s_waitcnt vmcnt(8)
.Lfirstit_4:
	s_waitcnt lgkmcnt(0)
	s_barrier
	s_setprio 1
	s_waitcnt lgkmcnt(0)
	v_mfma_f32_16x16x32_bf16 v[120:123], v[124:127], v[160:163], v[120:123]
	v_mfma_f32_16x16x32_bf16 v[128:131], v[136:139], v[160:163], v[128:131]
	v_mfma_f32_16x16x32_bf16 v[116:119], v[124:127], v[168:171], v[116:119]
	v_mfma_f32_16x16x32_bf16 v[112:115], v[136:139], v[168:171], v[112:115]
	v_mfma_f32_16x16x32_bf16 v[108:111], v[124:127], v[176:179], v[108:111]
	v_mfma_f32_16x16x32_bf16 v[104:107], v[136:139], v[176:179], v[104:107]
	v_mfma_f32_16x16x32_bf16 v[100:103], v[124:127], v[184:187], v[100:103]
	v_mfma_f32_16x16x32_bf16 v[96:99], v[136:139], v[184:187], v[96:99]
	v_mfma_f32_16x16x32_bf16 v[120:123], v[132:135], v[164:167], v[120:123]
	v_mfma_f32_16x16x32_bf16 v[128:131], v[140:143], v[164:167], v[128:131]
	v_mfma_f32_16x16x32_bf16 v[116:119], v[132:135], v[172:175], v[116:119]
	v_mfma_f32_16x16x32_bf16 v[112:115], v[140:143], v[172:175], v[112:115]
	v_mfma_f32_16x16x32_bf16 v[108:111], v[132:135], v[180:183], v[108:111]
	v_mfma_f32_16x16x32_bf16 v[104:107], v[140:143], v[180:183], v[104:107]
	v_mfma_f32_16x16x32_bf16 v[100:103], v[132:135], v[210:213], v[100:103]
	v_mfma_f32_16x16x32_bf16 v[96:99], v[140:143], v[210:213], v[96:99]
	s_setprio 0
	s_setprio 1
	v_mfma_f32_16x16x32_bf16 v[68:71], v[144:147], v[160:163], v[68:71]
	v_mfma_f32_16x16x32_bf16 v[60:63], v[152:155], v[160:163], v[60:63]
	v_mfma_f32_16x16x32_bf16 v[52:55], v[144:147], v[168:171], v[52:55]
	v_mfma_f32_16x16x32_bf16 v[48:51], v[152:155], v[168:171], v[48:51]
	v_mfma_f32_16x16x32_bf16 v[44:47], v[144:147], v[176:179], v[44:47]
	v_mfma_f32_16x16x32_bf16 v[40:43], v[152:155], v[176:179], v[40:43]
	v_mfma_f32_16x16x32_bf16 v[36:39], v[144:147], v[184:187], v[36:39]
	v_mfma_f32_16x16x32_bf16 v[32:35], v[152:155], v[184:187], v[32:35]
	v_mfma_f32_16x16x32_bf16 v[68:71], v[148:151], v[164:167], v[68:71]
	v_mfma_f32_16x16x32_bf16 v[60:63], v[156:159], v[164:167], v[60:63]
	v_mfma_f32_16x16x32_bf16 v[52:55], v[148:151], v[172:175], v[52:55]
	v_mfma_f32_16x16x32_bf16 v[48:51], v[156:159], v[172:175], v[48:51]
	v_mfma_f32_16x16x32_bf16 v[44:47], v[148:151], v[180:183], v[44:47]
	v_mfma_f32_16x16x32_bf16 v[40:43], v[156:159], v[180:183], v[40:43]
	v_mfma_f32_16x16x32_bf16 v[36:39], v[148:151], v[210:213], v[36:39]
	v_mfma_f32_16x16x32_bf16 v[32:35], v[156:159], v[210:213], v[32:35]
	s_setprio 0
	s_barrier
	s_add_i32 s15, s15, s62
	v_lshl_add_u64 v[198:199], s[8:9], 0, v[190:191]
	s_mov_b32 m0, s15
	ds_read_b128 v[160:163], v215 offset:16384
	ds_read_b128 v[164:167], v215 offset:17408
	ds_read_b128 v[168:171], v215 offset:18432
	ds_read_b128 v[172:175], v215 offset:19456
	ds_read_b128 v[176:179], v215 offset:20480
	ds_read_b128 v[180:183], v215 offset:21504
	ds_read_b128 v[184:187], v215 offset:22528
	ds_read_b128 v[210:213], v215 offset:23552
	global_load_lds_dwordx4 v[198:199], off
	s_add_i32 m0, s15, 0x2000
	s_add_u32 s16, s8, 0x40000
	v_lshl_add_u64 v[200:201], s[8:9], 0, v[194:195]
	s_addc_u32 s17, s9, 0
	s_add_i32 s15, s18, s62
	global_load_lds_dwordx4 v[200:201], off
	v_lshl_add_u64 v[216:217], s[16:17], 0, v[190:191]
	s_mov_b32 m0, s15
	v_lshl_add_u64 v[220:221], s[10:11], 0, v[192:193]
	global_load_lds_dwordx4 v[216:217], off
	v_lshl_add_u64 v[216:217], s[16:17], 0, v[194:195]
	s_add_i32 m0, s15, 0x2000
	s_nop 0
	global_load_lds_dwordx4 v[216:217], off
	v_lshl_add_u64 v[216:217], s[10:11], 0, v[188:189]
	s_mov_b32 m0, s63
	s_nop 0
	global_load_lds_dwordx4 v[216:217], off
	s_mov_b32 m0, s68
	s_nop 0
	global_load_lds_dwordx4 v[220:221], off
	s_waitcnt vmcnt(8)
	s_waitcnt lgkmcnt(0)
	s_barrier
; #define PG8_STAGE(bufoff, gbase, voff) do { _Pragma("unroll") for (int _i = 0; _i < 2; ++_i) \
;         __builtin_amdgcn_global_load_lds((const unsigned*)((const char*)(gbase) + (voff)[_i]), (LAS unsigned*)(lds + (bufoff) + ldsw + _i * 8192), 16, 0, 0); } while (0)
; #define PG8_LDA(dst, b, h) do { _Pragma("unroll") for (int m = 0; m < 4; ++m) _Pragma("unroll") for (int k = 0; k < 2; ++k) dst[m][k] = *(const LAS bf16x8*)(lds + PG8_SA(b, h) + aoff + m * 2048 + k * 1024); } while (0)
; #define PG8_LDB(dst, b, h) do { _Pragma("unroll") for (int n = 0; n < 2; ++n) _Pragma("unroll") for (int k = 0; k < 2; ++k) dst[n][k] = *(const LAS bf16x8*)(lds + PG8_SB(b, h) + boff + n * 2048 + k * 1024); } while (0)
; #define PG8_MMA(ai, bj, At, Bt) do { __builtin_amdgcn_s_setprio(1); _Pragma("unroll") for (int m = 0; m < 4; ++m) _Pragma("unroll") for (int n = 0; n < 2; ++n) _Pragma("unroll") for (int k = 0; k < 2; ++k) \
;         acc[ai][bj][m][n] = __builtin_amdgcn_mfma_f32_16x16x32_bf16(Bt[n][k], At[m][k], acc[ai][bj][m][n], 0, 0, 0); __builtin_amdgcn_s_setprio(0); } while (0)
; #define PG8_WAIT_V(n) asm volatile("s_waitcnt vmcnt(" #n ")" ::: "memory")
; #define PG8_WAIT_L(n) asm volatile("s_waitcnt lgkmcnt(" #n ")" ::: "memory")
; #define PG8_BAR __builtin_amdgcn_s_barrier()
; #define PG8_SCHED __builtin_amdgcn_sched_barrier(0)
; template <class Epi, class Sched>
; __device__ __forceinline__ void gemm_phase(LAS unsigned char* lds, const GemmP g, const Sched& S, const Epi& E, int tid) {
;     ...
;             PG8_WAIT_V(8); PG8_WAIT_L(0); PG8_BAR; PG8_MMA(1, 0, At, B0); PG8_MMA(1, 1, At, B1); PG8_BAR; PG8_SCHED;
;             PG8_LDB(B0, 1, 0); PG8_LDB(B1, 1, 1); PG8_SCHED; PG8_LDA(At, 1, 0); PG8_STAGE(PG8_SA(0, 1), a2 + hstepA, voffA);
;             PG8_WAIT_V(8); PG8_WAIT_L(0); PG8_BAR; PG8_MMA(0, 0, At, B0); PG8_MMA(0, 1, At, B1); PG8_BAR; PG8_SCHED;
	s_setprio 1
	s_waitcnt lgkmcnt(0)
	v_mfma_f32_16x16x32_bf16 v[92:95], v[124:127], v[160:163], v[92:95]
	v_mfma_f32_16x16x32_bf16 v[88:91], v[136:139], v[160:163], v[88:91]
	v_mfma_f32_16x16x32_bf16 v[84:87], v[124:127], v[168:171], v[84:87]
	v_mfma_f32_16x16x32_bf16 v[80:83], v[136:139], v[168:171], v[80:83]
	v_mfma_f32_16x16x32_bf16 v[76:79], v[124:127], v[176:179], v[76:79]
	v_mfma_f32_16x16x32_bf16 v[72:75], v[136:139], v[176:179], v[72:75]
	v_mfma_f32_16x16x32_bf16 v[64:67], v[124:127], v[184:187], v[64:67]
	v_mfma_f32_16x16x32_bf16 v[56:59], v[136:139], v[184:187], v[56:59]
	v_mfma_f32_16x16x32_bf16 v[92:95], v[132:135], v[164:167], v[92:95]
	v_mfma_f32_16x16x32_bf16 v[88:91], v[140:143], v[164:167], v[88:91]
	v_mfma_f32_16x16x32_bf16 v[84:87], v[132:135], v[172:175], v[84:87]
	v_mfma_f32_16x16x32_bf16 v[80:83], v[140:143], v[172:175], v[80:83]
	v_mfma_f32_16x16x32_bf16 v[76:79], v[132:135], v[180:183], v[76:79]
	v_mfma_f32_16x16x32_bf16 v[72:75], v[140:143], v[180:183], v[72:75]
	v_mfma_f32_16x16x32_bf16 v[64:67], v[132:135], v[210:213], v[64:67]
	v_mfma_f32_16x16x32_bf16 v[56:59], v[140:143], v[210:213], v[56:59]
	s_setprio 0
	s_setprio 1
	v_mfma_f32_16x16x32_bf16 v[28:31], v[144:147], v[160:163], v[28:31]
	v_mfma_f32_16x16x32_bf16 v[24:27], v[152:155], v[160:163], v[24:27]
	v_mfma_f32_16x16x32_bf16 v[20:23], v[144:147], v[168:171], v[20:23]
	v_mfma_f32_16x16x32_bf16 v[16:19], v[152:155], v[168:171], v[16:19]
	v_mfma_f32_16x16x32_bf16 v[12:15], v[144:147], v[176:179], v[12:15]
	v_mfma_f32_16x16x32_bf16 v[8:11], v[152:155], v[176:179], v[8:11]
	v_mfma_f32_16x16x32_bf16 v[4:7], v[144:147], v[184:187], v[4:7]
	v_mfma_f32_16x16x32_bf16 v[0:3], v[152:155], v[184:187], v[0:3]
	v_mfma_f32_16x16x32_bf16 v[28:31], v[148:151], v[164:167], v[28:31]
	v_mfma_f32_16x16x32_bf16 v[24:27], v[156:159], v[164:167], v[24:27]
	v_mfma_f32_16x16x32_bf16 v[20:23], v[148:151], v[172:175], v[20:23]
	v_mfma_f32_16x16x32_bf16 v[16:19], v[156:159], v[172:175], v[16:19]
	v_mfma_f32_16x16x32_bf16 v[12:15], v[148:151], v[180:183], v[12:15]
	v_mfma_f32_16x16x32_bf16 v[8:11], v[156:159], v[180:183], v[8:11]
	v_mfma_f32_16x16x32_bf16 v[4:7], v[148:151], v[210:213], v[4:7]
	v_mfma_f32_16x16x32_bf16 v[0:3], v[156:159], v[210:213], v[0:3]
	s_setprio 0
	s_barrier
	s_add_i32 s15, 0, 0x18000
	s_add_i32 s16, 0, 0x1c000
	v_add_u32_e32 v140, s15, v214
	v_add_u32_e32 v156, s16, v214
	ds_read_b128 v[124:127], v140
	ds_read_b128 v[132:135], v140 offset:1024
	ds_read_b128 v[136:139], v140 offset:2048
	ds_read_b128 v[140:143], v140 offset:3072
	ds_read_b128 v[144:147], v156
	ds_read_b128 v[148:151], v156 offset:1024
	ds_read_b128 v[152:155], v156 offset:2048
	ds_read_b128 v[156:159], v156 offset:3072
	s_add_u32 s10, s10, 0x40000
	s_addc_u32 s11, s11, 0
	s_mov_b32 m0, s69
	v_lshl_add_u64 v[222:223], s[10:11], 0, v[188:189]
	ds_read_b128 v[160:163], v215 offset:32768
	ds_read_b128 v[164:167], v215 offset:33792
	ds_read_b128 v[168:171], v215 offset:34816
	ds_read_b128 v[172:175], v215 offset:35840
	ds_read_b128 v[176:179], v215 offset:36864
	ds_read_b128 v[180:183], v215 offset:37888
	ds_read_b128 v[184:187], v215 offset:38912
	ds_read_b128 v[210:213], v215 offset:39936
	global_load_lds_dwordx4 v[222:223], off
	v_lshl_add_u64 v[222:223], s[10:11], 0, v[192:193]
	s_mov_b32 m0, s88
	s_nop 0
	global_load_lds_dwordx4 v[222:223], off
	s_waitcnt vmcnt(8)
	s_waitcnt lgkmcnt(0)
	s_barrier
	s_setprio 1
	s_waitcnt lgkmcnt(0)
	v_mfma_f32_16x16x32_bf16 v[120:123], v[124:127], v[160:163], v[120:123]
	v_mfma_f32_16x16x32_bf16 v[128:131], v[136:139], v[160:163], v[128:131]
	v_mfma_f32_16x16x32_bf16 v[116:119], v[124:127], v[168:171], v[116:119]
	v_mfma_f32_16x16x32_bf16 v[112:115], v[136:139], v[168:171], v[112:115]
	v_mfma_f32_16x16x32_bf16 v[108:111], v[124:127], v[176:179], v[108:111]
	v_mfma_f32_16x16x32_bf16 v[104:107], v[136:139], v[176:179], v[104:107]
	v_mfma_f32_16x16x32_bf16 v[100:103], v[124:127], v[184:187], v[100:103]
	v_mfma_f32_16x16x32_bf16 v[96:99], v[136:139], v[184:187], v[96:99]
	v_mfma_f32_16x16x32_bf16 v[120:123], v[132:135], v[164:167], v[120:123]
	v_mfma_f32_16x16x32_bf16 v[128:131], v[140:143], v[164:167], v[128:131]
	v_mfma_f32_16x16x32_bf16 v[116:119], v[132:135], v[172:175], v[116:119]
	v_mfma_f32_16x16x32_bf16 v[112:115], v[140:143], v[172:175], v[112:115]
	v_mfma_f32_16x16x32_bf16 v[108:111], v[132:135], v[180:183], v[108:111]
	v_mfma_f32_16x16x32_bf16 v[104:107], v[140:143], v[180:183], v[104:107]
	v_mfma_f32_16x16x32_bf16 v[100:103], v[132:135], v[210:213], v[100:103]
	v_mfma_f32_16x16x32_bf16 v[96:99], v[140:143], v[210:213], v[96:99]
	s_setprio 0
	s_setprio 1
	v_mfma_f32_16x16x32_bf16 v[68:71], v[144:147], v[160:163], v[68:71]
	v_mfma_f32_16x16x32_bf16 v[60:63], v[152:155], v[160:163], v[60:63]
	v_mfma_f32_16x16x32_bf16 v[52:55], v[144:147], v[168:171], v[52:55]
	v_mfma_f32_16x16x32_bf16 v[48:51], v[152:155], v[168:171], v[48:51]
	v_mfma_f32_16x16x32_bf16 v[44:47], v[144:147], v[176:179], v[44:47]
	v_mfma_f32_16x16x32_bf16 v[40:43], v[152:155], v[176:179], v[40:43]
	v_mfma_f32_16x16x32_bf16 v[36:39], v[144:147], v[184:187], v[36:39]
	v_mfma_f32_16x16x32_bf16 v[32:35], v[152:155], v[184:187], v[32:35]
	v_mfma_f32_16x16x32_bf16 v[68:71], v[148:151], v[164:167], v[68:71]
	v_mfma_f32_16x16x32_bf16 v[60:63], v[156:159], v[164:167], v[60:63]
	v_mfma_f32_16x16x32_bf16 v[52:55], v[148:151], v[172:175], v[52:55]
	v_mfma_f32_16x16x32_bf16 v[48:51], v[156:159], v[172:175], v[48:51]
	v_mfma_f32_16x16x32_bf16 v[44:47], v[148:151], v[180:183], v[44:47]
	v_mfma_f32_16x16x32_bf16 v[40:43], v[156:159], v[180:183], v[40:43]
	v_mfma_f32_16x16x32_bf16 v[36:39], v[148:151], v[210:213], v[36:39]
	v_mfma_f32_16x16x32_bf16 v[32:35], v[156:159], v[210:213], v[32:35]
	s_setprio 0
	s_barrier
; #define PG8_STAGE(bufoff, gbase, voff) do { _Pragma("unroll") for (int _i = 0; _i < 2; ++_i) \
;         __builtin_amdgcn_global_load_lds((const unsigned*)((const char*)(gbase) + (voff)[_i]), (LAS unsigned*)(lds + (bufoff) + ldsw + _i * 8192), 16, 0, 0); } while (0)
; #define PG8_LDA(dst, b, h) do { _Pragma("unroll") for (int m = 0; m < 4; ++m) _Pragma("unroll") for (int k = 0; k < 2; ++k) dst[m][k] = *(const LAS bf16x8*)(lds + PG8_SA(b, h) + aoff + m * 2048 + k * 1024); } while (0)
; #define PG8_MMA(ai, bj, At, Bt) do { __builtin_amdgcn_s_setprio(1); _Pragma("unroll") for (int m = 0; m < 4; ++m) _Pragma("unroll") for (int n = 0; n < 2; ++n) _Pragma("unroll") for (int k = 0; k < 2; ++k) \
;         acc[ai][bj][m][n] = __builtin_amdgcn_mfma_f32_16x16x32_bf16(Bt[n][k], At[m][k], acc[ai][bj][m][n], 0, 0, 0); __builtin_amdgcn_s_setprio(0); } while (0)
; #define PG8_WAIT_V(n) asm volatile("s_waitcnt vmcnt(" #n ")" ::: "memory")
; #define PG8_WAIT_L(n) asm volatile("s_waitcnt lgkmcnt(" #n ")" ::: "memory")
; #define PG8_BAR __builtin_amdgcn_s_barrier()
; #define PG8_SCHED __builtin_amdgcn_sched_barrier(0)
; template <class Epi, class Sched>
; __device__ __forceinline__ void gemm_phase(LAS unsigned char* lds, const GemmP g, const Sched& S, const Epi& E, int tid) {
;     ...
;             PG8_LDA(At, 1, 1); PG8_STAGE(PG8_SB(1, 0), b3, voffB); PG8_STAGE(PG8_SB(1, 1), b3 + hstepB, voffB); PG8_STAGE(PG8_SA(1, 0), a3, voffA);
;             PG8_WAIT_V(8); PG8_WAIT_L(0); PG8_BAR; PG8_MMA(1, 0, At, B0); PG8_MMA(1, 1, At, B1); PG8_BAR; PG8_SCHED;
;         }
;         if (wr == 0) PG8_BAR;
	s_add_i32 s10, s15, s62
	v_lshl_add_u64 v[198:199], v[198:199], 0, s[80:81]
	s_mov_b32 m0, s10
	ds_read_b128 v[160:163], v215 offset:49152
	ds_read_b128 v[164:167], v215 offset:50176
	ds_read_b128 v[168:171], v215 offset:51200
	ds_read_b128 v[172:175], v215 offset:52224
	ds_read_b128 v[176:179], v215 offset:53248
	ds_read_b128 v[180:183], v215 offset:54272
	ds_read_b128 v[184:187], v215 offset:55296
	ds_read_b128 v[210:213], v215 offset:56320
	global_load_lds_dwordx4 v[198:199], off
	s_add_i32 m0, s10, 0x2000
	s_add_u32 s8, s8, 0x40080
	v_lshl_add_u64 v[198:199], v[200:201], 0, s[80:81]
	s_addc_u32 s9, s9, 0
	s_add_i32 s10, s16, s62
	global_load_lds_dwordx4 v[198:199], off
	v_lshl_add_u64 v[198:199], s[8:9], 0, v[190:191]
	s_mov_b32 m0, s10
	s_nop 0
	global_load_lds_dwordx4 v[198:199], off
	v_lshl_add_u64 v[198:199], s[8:9], 0, v[194:195]
	s_add_i32 m0, s10, 0x2000
	s_nop 0
	global_load_lds_dwordx4 v[198:199], off
	v_lshl_add_u64 v[198:199], v[216:217], 0, s[80:81]
	s_mov_b32 m0, s82
	s_nop 0
	global_load_lds_dwordx4 v[198:199], off
	v_lshl_add_u64 v[198:199], v[220:221], 0, s[80:81]
	s_mov_b32 m0, s0
	s_nop 0
	global_load_lds_dwordx4 v[198:199], off
	s_waitcnt vmcnt(8)
	s_waitcnt lgkmcnt(0)
	s_barrier
	s_setprio 1
	s_waitcnt lgkmcnt(0)
	v_mfma_f32_16x16x32_bf16 v[92:95], v[124:127], v[160:163], v[92:95]
	v_mfma_f32_16x16x32_bf16 v[88:91], v[136:139], v[160:163], v[88:91]
	v_mfma_f32_16x16x32_bf16 v[84:87], v[124:127], v[168:171], v[84:87]
	v_mfma_f32_16x16x32_bf16 v[80:83], v[136:139], v[168:171], v[80:83]
	v_mfma_f32_16x16x32_bf16 v[76:79], v[124:127], v[176:179], v[76:79]
	v_mfma_f32_16x16x32_bf16 v[72:75], v[136:139], v[176:179], v[72:75]
	v_mfma_f32_16x16x32_bf16 v[64:67], v[124:127], v[184:187], v[64:67]
	v_mfma_f32_16x16x32_bf16 v[56:59], v[136:139], v[184:187], v[56:59]
	v_mfma_f32_16x16x32_bf16 v[92:95], v[132:135], v[164:167], v[92:95]
	v_mfma_f32_16x16x32_bf16 v[88:91], v[140:143], v[164:167], v[88:91]
	v_mfma_f32_16x16x32_bf16 v[84:87], v[132:135], v[172:175], v[84:87]
	v_mfma_f32_16x16x32_bf16 v[80:83], v[140:143], v[172:175], v[80:83]
	v_mfma_f32_16x16x32_bf16 v[76:79], v[132:135], v[180:183], v[76:79]
	v_mfma_f32_16x16x32_bf16 v[72:75], v[140:143], v[180:183], v[72:75]
	v_mfma_f32_16x16x32_bf16 v[64:67], v[132:135], v[210:213], v[64:67]
	v_mfma_f32_16x16x32_bf16 v[56:59], v[140:143], v[210:213], v[56:59]
	s_setprio 0
	s_setprio 1
	v_mfma_f32_16x16x32_bf16 v[28:31], v[144:147], v[160:163], v[28:31]
	v_mfma_f32_16x16x32_bf16 v[24:27], v[152:155], v[160:163], v[24:27]
	v_mfma_f32_16x16x32_bf16 v[20:23], v[144:147], v[168:171], v[20:23]
	v_mfma_f32_16x16x32_bf16 v[16:19], v[152:155], v[168:171], v[16:19]
	v_mfma_f32_16x16x32_bf16 v[12:15], v[144:147], v[176:179], v[12:15]
	v_mfma_f32_16x16x32_bf16 v[8:11], v[152:155], v[176:179], v[8:11]
	v_mfma_f32_16x16x32_bf16 v[4:7], v[144:147], v[184:187], v[4:7]
	v_mfma_f32_16x16x32_bf16 v[0:3], v[152:155], v[184:187], v[0:3]
	v_mfma_f32_16x16x32_bf16 v[28:31], v[148:151], v[164:167], v[28:31]
	v_mfma_f32_16x16x32_bf16 v[24:27], v[156:159], v[164:167], v[24:27]
	v_mfma_f32_16x16x32_bf16 v[20:23], v[148:151], v[172:175], v[20:23]
	v_mfma_f32_16x16x32_bf16 v[16:19], v[156:159], v[172:175], v[16:19]
	v_mfma_f32_16x16x32_bf16 v[12:15], v[148:151], v[180:183], v[12:15]
	v_mfma_f32_16x16x32_bf16 v[8:11], v[156:159], v[180:183], v[8:11]
	v_mfma_f32_16x16x32_bf16 v[4:7], v[148:151], v[210:213], v[4:7]
	v_mfma_f32_16x16x32_bf16 v[0:3], v[156:159], v[210:213], v[0:3]
	s_setprio 0
	s_barrier
	s_add_i32 s14, s14, 2
	s_add_u32 s12, s12, 0x100
	s_addc_u32 s13, s13, 0
	s_add_u32 s6, s6, 0x100
	s_addc_u32 s7, s7, 0
	s_cmp_gt_u32 s14, 13
	s_cbranch_scc0 .LBB0_1163
	s_and_b64 vcc, exec, s[78:79]
	s_cbranch_vccz .LBB0_1166
	s_barrier

; #define PG8_STAGE(bufoff, gbase, voff) do { _Pragma("unroll") for (int _i = 0; _i < 2; ++_i) \
;         __builtin_amdgcn_global_load_lds((const unsigned*)((const char*)(gbase) + (voff)[_i]), (LAS unsigned*)(lds + (bufoff) + ldsw + _i * 8192), 16, 0, 0); } while (0)
; #define PG8_LDA(dst, b, h) do { _Pragma("unroll") for (int m = 0; m < 4; ++m) _Pragma("unroll") for (int k = 0; k < 2; ++k) dst[m][k] = *(const LAS bf16x8*)(lds + PG8_SA(b, h) + aoff + m * 2048 + k * 1024); } while (0)
; #define PG8_LDB(dst, b, h) do { _Pragma("unroll") for (int n = 0; n < 2; ++n) _Pragma("unroll") for (int k = 0; k < 2; ++k) dst[n][k] = *(const LAS bf16x8*)(lds + PG8_SB(b, h) + boff + n * 2048 + k * 1024); } while (0)
; #define PG8_MMA(ai, bj, At, Bt) do { __builtin_amdgcn_s_setprio(1); _Pragma("unroll") for (int m = 0; m < 4; ++m) _Pragma("unroll") for (int n = 0; n < 2; ++n) _Pragma("unroll") for (int k = 0; k < 2; ++k) \
;         acc[ai][bj][m][n] = __builtin_amdgcn_mfma_f32_16x16x32_bf16(Bt[n][k], At[m][k], acc[ai][bj][m][n], 0, 0, 0); __builtin_amdgcn_s_setprio(0); } while (0)
; #define PG8_WAIT_V(n) asm volatile("s_waitcnt vmcnt(" #n ")" ::: "memory")
; #define PG8_WAIT_L(n) asm volatile("s_waitcnt lgkmcnt(" #n ")" ::: "memory")
; #define PG8_BAR __builtin_amdgcn_s_barrier()
; #define PG8_SCHED __builtin_amdgcn_sched_barrier(0)
; template <class Epi, class Sched>
; __device__ __forceinline__ void gemm_phase(LAS unsigned char* lds, const GemmP g, const Sched& S, const Epi& E, int tid) {
;     ...
;         for (int t = 0; t < nt; t += 2) {
;             const bool last = (t == nt - 2);
;             const char* a1 = cA + (size_t)(t + 1) * kstep;
;             const char* a2 = last ? nA : cA + (size_t)(t + 2) * kstep; const char* b2 = last ? nB : cB + (size_t)(t + 2) * kstep;
;             const char* a3 = a2 + kstep; const char* b3 = b2 + kstep;
;             PG8_LDB(B0, 0, 0); PG8_LDB(B1, 0, 1); PG8_SCHED; PG8_LDA(At, 0, 0); PG8_STAGE(PG8_SA(1, 1), a1 + hstepA, voffA);
;             PG8_WAIT_V(8); PG8_WAIT_L(0); PG8_BAR; PG8_MMA(0, 0, At, B0); PG8_MMA(0, 1, At, B1); PG8_BAR; PG8_SCHED;
;             PG8_LDA(At, 0, 1); PG8_STAGE(PG8_SB(0, 0), b2, voffB); PG8_STAGE(PG8_SB(0, 1), b2 + hstepB, voffB); PG8_STAGE(PG8_SA(0, 0), a2, voffA);
.LBB0_1390:
	s_add_u32 s10, s6, 0xfffc0080
	s_addc_u32 s11, s7, -1
	s_add_i32 s39, 0, 0x10000
	s_cmp_eq_u32 s38, 12
	s_cselect_b32 s13, s95, s11
	s_cselect_b32 s12, s94, s10
	v_add_u32_e32 v144, s39, v146
	s_cselect_b32 s11, s97, s15
	s_cselect_b32 s10, s96, s14
	s_add_i32 s56, 0, 0x14000
	ds_read_b128 v[140:143], v144
	ds_read_b128 v[148:151], v144 offset:1024
	ds_read_b128 v[152:155], v144 offset:2048
	ds_read_b128 v[156:159], v144 offset:3072
	v_add_u32_e32 v144, s56, v146
	ds_read_b128 v[160:163], v144
	ds_read_b128 v[164:167], v144 offset:1024
	ds_read_b128 v[168:171], v144 offset:2048
	ds_read_b128 v[172:175], v144 offset:3072
	v_lshl_add_u64 v[144:145], s[6:7], 0, v[138:139]
	s_add_i32 m0, s53, 0xc000
	ds_read_b128 v[176:179], v147
	ds_read_b128 v[180:183], v147 offset:1024
	ds_read_b128 v[184:187], v147 offset:2048
	ds_read_b128 v[188:191], v147 offset:3072
	ds_read_b128 v[192:195], v147 offset:4096
	ds_read_b128 v[206:209], v147 offset:5120
	ds_read_b128 v[210:213], v147 offset:6144
	ds_read_b128 v[214:217], v147 offset:7168
	global_load_lds_dwordx4 v[144:145], off
	v_lshl_add_u64 v[144:145], s[6:7], 0, v[136:137]
	s_add_i32 m0, s53, 0xe000
	s_nop 0
	global_load_lds_dwordx4 v[144:145], off
	s_cmp_eq_u32 s38, -2
	s_cbranch_scc1 .Lfirstit_5
	s_waitcnt vmcnt(8)
.Lfirstit_5:
	s_waitcnt lgkmcnt(0)
	s_barrier
	s_setprio 1
	s_waitcnt lgkmcnt(0)
	v_mfma_f32_16x16x32_bf16 v[92:95], v[140:143], v[176:179], v[92:95]
	v_mfma_f32_16x16x32_bf16 v[88:91], v[152:155], v[176:179], v[88:91]
	v_mfma_f32_16x16x32_bf16 v[76:79], v[140:143], v[184:187], v[76:79]
	v_mfma_f32_16x16x32_bf16 v[72:75], v[152:155], v[184:187], v[72:75]
	v_mfma_f32_16x16x32_bf16 v[60:63], v[140:143], v[192:195], v[60:63]
	v_mfma_f32_16x16x32_bf16 v[56:59], v[152:155], v[192:195], v[56:59]
	v_mfma_f32_16x16x32_bf16 v[124:127], v[140:143], v[210:213], v[124:127]
	v_mfma_f32_16x16x32_bf16 v[120:123], v[152:155], v[210:213], v[120:123]
	v_mfma_f32_16x16x32_bf16 v[92:95], v[148:151], v[180:183], v[92:95]
	v_mfma_f32_16x16x32_bf16 v[88:91], v[156:159], v[180:183], v[88:91]
	v_mfma_f32_16x16x32_bf16 v[76:79], v[148:151], v[188:191], v[76:79]
	v_mfma_f32_16x16x32_bf16 v[72:75], v[156:159], v[188:191], v[72:75]
	v_mfma_f32_16x16x32_bf16 v[60:63], v[148:151], v[206:209], v[60:63]
	v_mfma_f32_16x16x32_bf16 v[56:59], v[156:159], v[206:209], v[56:59]
	v_mfma_f32_16x16x32_bf16 v[124:127], v[148:151], v[214:217], v[124:127]
	v_mfma_f32_16x16x32_bf16 v[120:123], v[156:159], v[214:217], v[120:123]
	s_setprio 0
	s_setprio 1
	v_mfma_f32_16x16x32_bf16 v[84:87], v[160:163], v[176:179], v[84:87]
	v_mfma_f32_16x16x32_bf16 v[80:83], v[168:171], v[176:179], v[80:83]
	v_mfma_f32_16x16x32_bf16 v[68:71], v[160:163], v[184:187], v[68:71]
	v_mfma_f32_16x16x32_bf16 v[64:67], v[168:171], v[184:187], v[64:67]
	v_mfma_f32_16x16x32_bf16 v[52:55], v[160:163], v[192:195], v[52:55]
	v_mfma_f32_16x16x32_bf16 v[48:51], v[168:171], v[192:195], v[48:51]
	v_mfma_f32_16x16x32_bf16 v[116:119], v[160:163], v[210:213], v[116:119]
	v_mfma_f32_16x16x32_bf16 v[112:115], v[168:171], v[210:213], v[112:115]
	v_mfma_f32_16x16x32_bf16 v[84:87], v[164:167], v[180:183], v[84:87]
	v_mfma_f32_16x16x32_bf16 v[80:83], v[172:175], v[180:183], v[80:83]
	v_mfma_f32_16x16x32_bf16 v[68:71], v[164:167], v[188:191], v[68:71]
	v_mfma_f32_16x16x32_bf16 v[64:67], v[172:175], v[188:191], v[64:67]
	v_mfma_f32_16x16x32_bf16 v[52:55], v[164:167], v[206:209], v[52:55]
	v_mfma_f32_16x16x32_bf16 v[48:51], v[172:175], v[206:209], v[48:51]
	v_mfma_f32_16x16x32_bf16 v[116:119], v[164:167], v[214:217], v[116:119]
	v_mfma_f32_16x16x32_bf16 v[112:115], v[172:175], v[214:217], v[112:115]
	s_setprio 0
	s_barrier
	s_add_i32 s39, s39, s52
	v_lshl_add_u64 v[144:145], s[10:11], 0, v[130:131]
	s_mov_b32 m0, s39
	ds_read_b128 v[176:179], v147 offset:16384
	ds_read_b128 v[180:183], v147 offset:17408
	ds_read_b128 v[184:187], v147 offset:18432
	ds_read_b128 v[188:191], v147 offset:19456
	ds_read_b128 v[192:195], v147 offset:20480
	ds_read_b128 v[206:209], v147 offset:21504
	ds_read_b128 v[210:213], v147 offset:22528
	ds_read_b128 v[214:217], v147 offset:23552
	global_load_lds_dwordx4 v[144:145], off
	s_add_i32 m0, s39, 0x2000
	s_add_u32 s48, s10, 0x40000
	v_lshl_add_u64 v[198:199], s[10:11], 0, v[134:135]
	s_addc_u32 s49, s11, 0
	s_add_i32 s39, s56, s52
	global_load_lds_dwordx4 v[198:199], off
	v_lshl_add_u64 v[200:201], s[48:49], 0, v[130:131]
	s_mov_b32 m0, s39
	v_lshl_add_u64 v[220:221], s[12:13], 0, v[132:133]
	global_load_lds_dwordx4 v[200:201], off
	v_lshl_add_u64 v[200:201], s[48:49], 0, v[134:135]
	s_add_i32 m0, s39, 0x2000
	s_nop 0
	global_load_lds_dwordx4 v[200:201], off
	v_lshl_add_u64 v[200:201], s[12:13], 0, v[128:129]
	s_mov_b32 m0, s53
	s_nop 0
	global_load_lds_dwordx4 v[200:201], off
	s_mov_b32 m0, s54
	s_nop 0
	global_load_lds_dwordx4 v[220:221], off
	s_waitcnt vmcnt(8)
	s_waitcnt lgkmcnt(0)
	s_barrier
; #define PG8_STAGE(bufoff, gbase, voff) do { _Pragma("unroll") for (int _i = 0; _i < 2; ++_i) \
;         __builtin_amdgcn_global_load_lds((const unsigned*)((const char*)(gbase) + (voff)[_i]), (LAS unsigned*)(lds + (bufoff) + ldsw + _i * 8192), 16, 0, 0); } while (0)
; #define PG8_LDA(dst, b, h) do { _Pragma("unroll") for (int m = 0; m < 4; ++m) _Pragma("unroll") for (int k = 0; k < 2; ++k) dst[m][k] = *(const LAS bf16x8*)(lds + PG8_SA(b, h) + aoff + m * 2048 + k * 1024); } while (0)
; #define PG8_LDB(dst, b, h) do { _Pragma("unroll") for (int n = 0; n < 2; ++n) _Pragma("unroll") for (int k = 0; k < 2; ++k) dst[n][k] = *(const LAS bf16x8*)(lds + PG8_SB(b, h) + boff + n * 2048 + k * 1024); } while (0)
; #define PG8_MMA(ai, bj, At, Bt) do { __builtin_amdgcn_s_setprio(1); _Pragma("unroll") for (int m = 0; m < 4; ++m) _Pragma("unroll") for (int n = 0; n < 2; ++n) _Pragma("unroll") for (int k = 0; k < 2; ++k) \
;         acc[ai][bj][m][n] = __builtin_amdgcn_mfma_f32_16x16x32_bf16(Bt[n][k], At[m][k], acc[ai][bj][m][n], 0, 0, 0); __builtin_amdgcn_s_setprio(0); } while (0)
; #define PG8_WAIT_V(n) asm volatile("s_waitcnt vmcnt(" #n ")" ::: "memory")
; #define PG8_WAIT_L(n) asm volatile("s_waitcnt lgkmcnt(" #n ")" ::: "memory")
; #define PG8_BAR __builtin_amdgcn_s_barrier()
; #define PG8_SCHED __builtin_amdgcn_sched_barrier(0)
; template <class Epi, class Sched>
; __device__ __forceinline__ void gemm_phase(LAS unsigned char* lds, const GemmP g, const Sched& S, const Epi& E, int tid) {
;     ...
;             PG8_WAIT_V(8); PG8_WAIT_L(0); PG8_BAR; PG8_MMA(1, 0, At, B0); PG8_MMA(1, 1, At, B1); PG8_BAR; PG8_SCHED;
;             PG8_LDB(B0, 1, 0); PG8_LDB(B1, 1, 1); PG8_SCHED; PG8_LDA(At, 1, 0); PG8_STAGE(PG8_SA(0, 1), a2 + hstepA, voffA);
;             PG8_WAIT_V(8); PG8_WAIT_L(0); PG8_BAR; PG8_MMA(0, 0, At, B0); PG8_MMA(0, 1, At, B1); PG8_BAR; PG8_SCHED;
	s_setprio 1
	s_waitcnt lgkmcnt(0)
	v_mfma_f32_16x16x32_bf16 v[44:47], v[140:143], v[176:179], v[44:47]
	v_mfma_f32_16x16x32_bf16 v[40:43], v[152:155], v[176:179], v[40:43]
	v_mfma_f32_16x16x32_bf16 v[28:31], v[140:143], v[184:187], v[28:31]
	v_mfma_f32_16x16x32_bf16 v[24:27], v[152:155], v[184:187], v[24:27]
	v_mfma_f32_16x16x32_bf16 v[12:15], v[140:143], v[192:195], v[12:15]
	v_mfma_f32_16x16x32_bf16 v[8:11], v[152:155], v[192:195], v[8:11]
	v_mfma_f32_16x16x32_bf16 v[108:111], v[140:143], v[210:213], v[108:111]
	v_mfma_f32_16x16x32_bf16 v[104:107], v[152:155], v[210:213], v[104:107]
	v_mfma_f32_16x16x32_bf16 v[44:47], v[148:151], v[180:183], v[44:47]
	v_mfma_f32_16x16x32_bf16 v[40:43], v[156:159], v[180:183], v[40:43]
	v_mfma_f32_16x16x32_bf16 v[28:31], v[148:151], v[188:191], v[28:31]
	v_mfma_f32_16x16x32_bf16 v[24:27], v[156:159], v[188:191], v[24:27]
	v_mfma_f32_16x16x32_bf16 v[12:15], v[148:151], v[206:209], v[12:15]
	v_mfma_f32_16x16x32_bf16 v[8:11], v[156:159], v[206:209], v[8:11]
	v_mfma_f32_16x16x32_bf16 v[108:111], v[148:151], v[214:217], v[108:111]
	v_mfma_f32_16x16x32_bf16 v[104:107], v[156:159], v[214:217], v[104:107]
	s_setprio 0
	s_setprio 1
	v_mfma_f32_16x16x32_bf16 v[36:39], v[160:163], v[176:179], v[36:39]
	v_mfma_f32_16x16x32_bf16 v[32:35], v[168:171], v[176:179], v[32:35]
	v_mfma_f32_16x16x32_bf16 v[20:23], v[160:163], v[184:187], v[20:23]
	v_mfma_f32_16x16x32_bf16 v[16:19], v[168:171], v[184:187], v[16:19]
	v_mfma_f32_16x16x32_bf16 v[4:7], v[160:163], v[192:195], v[4:7]
	v_mfma_f32_16x16x32_bf16 v[0:3], v[168:171], v[192:195], v[0:3]
	v_mfma_f32_16x16x32_bf16 v[100:103], v[160:163], v[210:213], v[100:103]
	v_mfma_f32_16x16x32_bf16 v[96:99], v[168:171], v[210:213], v[96:99]
	v_mfma_f32_16x16x32_bf16 v[36:39], v[164:167], v[180:183], v[36:39]
	v_mfma_f32_16x16x32_bf16 v[32:35], v[172:175], v[180:183], v[32:35]
	v_mfma_f32_16x16x32_bf16 v[20:23], v[164:167], v[188:191], v[20:23]
	v_mfma_f32_16x16x32_bf16 v[16:19], v[172:175], v[188:191], v[16:19]
	v_mfma_f32_16x16x32_bf16 v[4:7], v[164:167], v[206:209], v[4:7]
	v_mfma_f32_16x16x32_bf16 v[0:3], v[172:175], v[206:209], v[0:3]
	v_mfma_f32_16x16x32_bf16 v[100:103], v[164:167], v[214:217], v[100:103]
	v_mfma_f32_16x16x32_bf16 v[96:99], v[172:175], v[214:217], v[96:99]
	s_setprio 0
	s_barrier
	s_add_i32 s39, 0, 0x18000
	s_add_i32 s48, 0, 0x1c000
	v_add_u32_e32 v156, s39, v146
	v_add_u32_e32 v172, s48, v146
	ds_read_b128 v[140:143], v156
	ds_read_b128 v[148:151], v156 offset:1024
	ds_read_b128 v[152:155], v156 offset:2048
	ds_read_b128 v[156:159], v156 offset:3072
	ds_read_b128 v[160:163], v172
	ds_read_b128 v[164:167], v172 offset:1024
	ds_read_b128 v[168:171], v172 offset:2048
	ds_read_b128 v[172:175], v172 offset:3072
	s_add_u32 s12, s12, 0x40000
	s_addc_u32 s13, s13, 0
	s_mov_b32 m0, s58
	v_lshl_add_u64 v[222:223], s[12:13], 0, v[128:129]
	ds_read_b128 v[176:179], v147 offset:32768
	ds_read_b128 v[180:183], v147 offset:33792
	ds_read_b128 v[184:187], v147 offset:34816
	ds_read_b128 v[188:191], v147 offset:35840
	ds_read_b128 v[192:195], v147 offset:36864
	ds_read_b128 v[206:209], v147 offset:37888
	ds_read_b128 v[210:213], v147 offset:38912
	ds_read_b128 v[214:217], v147 offset:39936
	global_load_lds_dwordx4 v[222:223], off
	v_lshl_add_u64 v[222:223], s[12:13], 0, v[132:133]
	s_mov_b32 m0, s59
	s_nop 0
	global_load_lds_dwordx4 v[222:223], off
	s_waitcnt vmcnt(8)
	s_waitcnt lgkmcnt(0)
	s_barrier
	s_setprio 1
	s_waitcnt lgkmcnt(0)
	v_mfma_f32_16x16x32_bf16 v[92:95], v[140:143], v[176:179], v[92:95]
	v_mfma_f32_16x16x32_bf16 v[88:91], v[152:155], v[176:179], v[88:91]
	v_mfma_f32_16x16x32_bf16 v[76:79], v[140:143], v[184:187], v[76:79]
	v_mfma_f32_16x16x32_bf16 v[72:75], v[152:155], v[184:187], v[72:75]
	v_mfma_f32_16x16x32_bf16 v[60:63], v[140:143], v[192:195], v[60:63]
	v_mfma_f32_16x16x32_bf16 v[56:59], v[152:155], v[192:195], v[56:59]
	v_mfma_f32_16x16x32_bf16 v[124:127], v[140:143], v[210:213], v[124:127]
	v_mfma_f32_16x16x32_bf16 v[120:123], v[152:155], v[210:213], v[120:123]
	v_mfma_f32_16x16x32_bf16 v[92:95], v[148:151], v[180:183], v[92:95]
	v_mfma_f32_16x16x32_bf16 v[88:91], v[156:159], v[180:183], v[88:91]
	v_mfma_f32_16x16x32_bf16 v[76:79], v[148:151], v[188:191], v[76:79]
	v_mfma_f32_16x16x32_bf16 v[72:75], v[156:159], v[188:191], v[72:75]
	v_mfma_f32_16x16x32_bf16 v[60:63], v[148:151], v[206:209], v[60:63]
	v_mfma_f32_16x16x32_bf16 v[56:59], v[156:159], v[206:209], v[56:59]
	v_mfma_f32_16x16x32_bf16 v[124:127], v[148:151], v[214:217], v[124:127]
	v_mfma_f32_16x16x32_bf16 v[120:123], v[156:159], v[214:217], v[120:123]
	s_setprio 0
	s_setprio 1
	v_mfma_f32_16x16x32_bf16 v[84:87], v[160:163], v[176:179], v[84:87]
	v_mfma_f32_16x16x32_bf16 v[80:83], v[168:171], v[176:179], v[80:83]
	v_mfma_f32_16x16x32_bf16 v[68:71], v[160:163], v[184:187], v[68:71]
	v_mfma_f32_16x16x32_bf16 v[64:67], v[168:171], v[184:187], v[64:67]
	v_mfma_f32_16x16x32_bf16 v[52:55], v[160:163], v[192:195], v[52:55]
	v_mfma_f32_16x16x32_bf16 v[48:51], v[168:171], v[192:195], v[48:51]
	v_mfma_f32_16x16x32_bf16 v[116:119], v[160:163], v[210:213], v[116:119]
	v_mfma_f32_16x16x32_bf16 v[112:115], v[168:171], v[210:213], v[112:115]
	v_mfma_f32_16x16x32_bf16 v[84:87], v[164:167], v[180:183], v[84:87]
	v_mfma_f32_16x16x32_bf16 v[80:83], v[172:175], v[180:183], v[80:83]
	v_mfma_f32_16x16x32_bf16 v[68:71], v[164:167], v[188:191], v[68:71]
	v_mfma_f32_16x16x32_bf16 v[64:67], v[172:175], v[188:191], v[64:67]
	v_mfma_f32_16x16x32_bf16 v[52:55], v[164:167], v[206:209], v[52:55]
	v_mfma_f32_16x16x32_bf16 v[48:51], v[172:175], v[206:209], v[48:51]
	v_mfma_f32_16x16x32_bf16 v[116:119], v[164:167], v[214:217], v[116:119]
	v_mfma_f32_16x16x32_bf16 v[112:115], v[172:175], v[214:217], v[112:115]
	s_setprio 0
	s_barrier
; #define PG8_STAGE(bufoff, gbase, voff) do { _Pragma("unroll") for (int _i = 0; _i < 2; ++_i) \
;         __builtin_amdgcn_global_load_lds((const unsigned*)((const char*)(gbase) + (voff)[_i]), (LAS unsigned*)(lds + (bufoff) + ldsw + _i * 8192), 16, 0, 0); } while (0)
; #define PG8_LDA(dst, b, h) do { _Pragma("unroll") for (int m = 0; m < 4; ++m) _Pragma("unroll") for (int k = 0; k < 2; ++k) dst[m][k] = *(const LAS bf16x8*)(lds + PG8_SA(b, h) + aoff + m * 2048 + k * 1024); } while (0)
; #define PG8_MMA(ai, bj, At, Bt) do { __builtin_amdgcn_s_setprio(1); _Pragma("unroll") for (int m = 0; m < 4; ++m) _Pragma("unroll") for (int n = 0; n < 2; ++n) _Pragma("unroll") for (int k = 0; k < 2; ++k) \
;         acc[ai][bj][m][n] = __builtin_amdgcn_mfma_f32_16x16x32_bf16(Bt[n][k], At[m][k], acc[ai][bj][m][n], 0, 0, 0); __builtin_amdgcn_s_setprio(0); } while (0)
; #define PG8_WAIT_V(n) asm volatile("s_waitcnt vmcnt(" #n ")" ::: "memory")
; #define PG8_WAIT_L(n) asm volatile("s_waitcnt lgkmcnt(" #n ")" ::: "memory")
; #define PG8_BAR __builtin_amdgcn_s_barrier()
; #define PG8_SCHED __builtin_amdgcn_sched_barrier(0)
; template <class Epi, class Sched>
; __device__ __forceinline__ void gemm_phase(LAS unsigned char* lds, const GemmP g, const Sched& S, const Epi& E, int tid) {
;     ...
;             PG8_LDA(At, 1, 1); PG8_STAGE(PG8_SB(1, 0), b3, voffB); PG8_STAGE(PG8_SB(1, 1), b3 + hstepB, voffB); PG8_STAGE(PG8_SA(1, 0), a3, voffA);
;             PG8_WAIT_V(8); PG8_WAIT_L(0); PG8_BAR; PG8_MMA(1, 0, At, B0); PG8_MMA(1, 1, At, B1); PG8_BAR; PG8_SCHED;
;         }
;         if (wr == 0) PG8_BAR;
	s_add_i32 s12, s39, s52
	v_lshl_add_u64 v[144:145], v[144:145], 0, s[80:81]
	s_mov_b32 m0, s12
	ds_read_b128 v[176:179], v147 offset:49152
	ds_read_b128 v[180:183], v147 offset:50176
	ds_read_b128 v[184:187], v147 offset:51200
	ds_read_b128 v[188:191], v147 offset:52224
	ds_read_b128 v[192:195], v147 offset:53248
	ds_read_b128 v[206:209], v147 offset:54272
	ds_read_b128 v[210:213], v147 offset:55296
	ds_read_b128 v[214:217], v147 offset:56320
	global_load_lds_dwordx4 v[144:145], off
	s_add_i32 m0, s12, 0x2000
	s_add_u32 s10, s10, 0x40080
	v_lshl_add_u64 v[144:145], v[198:199], 0, s[80:81]
	s_addc_u32 s11, s11, 0
	s_add_i32 s12, s48, s52
	global_load_lds_dwordx4 v[144:145], off
	v_lshl_add_u64 v[144:145], s[10:11], 0, v[130:131]
	s_mov_b32 m0, s12
	s_nop 0
	global_load_lds_dwordx4 v[144:145], off
	v_lshl_add_u64 v[144:145], s[10:11], 0, v[134:135]
	s_add_i32 m0, s12, 0x2000
	s_nop 0
	global_load_lds_dwordx4 v[144:145], off
	v_lshl_add_u64 v[144:145], v[200:201], 0, s[80:81]
	s_mov_b32 m0, s89
	s_nop 0
	global_load_lds_dwordx4 v[144:145], off
	v_lshl_add_u64 v[144:145], v[220:221], 0, s[80:81]
	s_mov_b32 m0, s64
	s_nop 0
	global_load_lds_dwordx4 v[144:145], off
	s_waitcnt vmcnt(8)
	s_waitcnt lgkmcnt(0)
	s_barrier
	s_setprio 1
	s_waitcnt lgkmcnt(0)
	v_mfma_f32_16x16x32_bf16 v[44:47], v[140:143], v[176:179], v[44:47]
	v_mfma_f32_16x16x32_bf16 v[40:43], v[152:155], v[176:179], v[40:43]
	v_mfma_f32_16x16x32_bf16 v[28:31], v[140:143], v[184:187], v[28:31]
	v_mfma_f32_16x16x32_bf16 v[24:27], v[152:155], v[184:187], v[24:27]
	v_mfma_f32_16x16x32_bf16 v[12:15], v[140:143], v[192:195], v[12:15]
	v_mfma_f32_16x16x32_bf16 v[8:11], v[152:155], v[192:195], v[8:11]
	v_mfma_f32_16x16x32_bf16 v[108:111], v[140:143], v[210:213], v[108:111]
	v_mfma_f32_16x16x32_bf16 v[104:107], v[152:155], v[210:213], v[104:107]
	v_mfma_f32_16x16x32_bf16 v[44:47], v[148:151], v[180:183], v[44:47]
	v_mfma_f32_16x16x32_bf16 v[40:43], v[156:159], v[180:183], v[40:43]
	v_mfma_f32_16x16x32_bf16 v[28:31], v[148:151], v[188:191], v[28:31]
	v_mfma_f32_16x16x32_bf16 v[24:27], v[156:159], v[188:191], v[24:27]
	v_mfma_f32_16x16x32_bf16 v[12:15], v[148:151], v[206:209], v[12:15]
	v_mfma_f32_16x16x32_bf16 v[8:11], v[156:159], v[206:209], v[8:11]
	v_mfma_f32_16x16x32_bf16 v[108:111], v[148:151], v[214:217], v[108:111]
	v_mfma_f32_16x16x32_bf16 v[104:107], v[156:159], v[214:217], v[104:107]
	s_setprio 0
	s_setprio 1
	v_mfma_f32_16x16x32_bf16 v[36:39], v[160:163], v[176:179], v[36:39]
	v_mfma_f32_16x16x32_bf16 v[32:35], v[168:171], v[176:179], v[32:35]
	v_mfma_f32_16x16x32_bf16 v[20:23], v[160:163], v[184:187], v[20:23]
	v_mfma_f32_16x16x32_bf16 v[16:19], v[168:171], v[184:187], v[16:19]
	v_mfma_f32_16x16x32_bf16 v[4:7], v[160:163], v[192:195], v[4:7]
	v_mfma_f32_16x16x32_bf16 v[0:3], v[168:171], v[192:195], v[0:3]
	v_mfma_f32_16x16x32_bf16 v[100:103], v[160:163], v[210:213], v[100:103]
	v_mfma_f32_16x16x32_bf16 v[96:99], v[168:171], v[210:213], v[96:99]
	v_mfma_f32_16x16x32_bf16 v[36:39], v[164:167], v[180:183], v[36:39]
	v_mfma_f32_16x16x32_bf16 v[32:35], v[172:175], v[180:183], v[32:35]
	v_mfma_f32_16x16x32_bf16 v[20:23], v[164:167], v[188:191], v[20:23]
	v_mfma_f32_16x16x32_bf16 v[16:19], v[172:175], v[188:191], v[16:19]
	v_mfma_f32_16x16x32_bf16 v[4:7], v[164:167], v[206:209], v[4:7]
	v_mfma_f32_16x16x32_bf16 v[0:3], v[172:175], v[206:209], v[0:3]
	v_mfma_f32_16x16x32_bf16 v[100:103], v[164:167], v[214:217], v[100:103]
	v_mfma_f32_16x16x32_bf16 v[96:99], v[172:175], v[214:217], v[96:99]
	s_setprio 0
	s_barrier
	s_add_i32 s38, s38, 2
	s_add_u32 s14, s14, 0x100
	s_addc_u32 s15, s15, 0
	s_add_u32 s6, s6, 0x100
	s_addc_u32 s7, s7, 0
	s_cmp_gt_u32 s38, 13
	s_cbranch_scc0 .LBB0_1390
	s_and_b64 vcc, exec, s[2:3]
	s_cbranch_vccz .LBB0_1393
	s_barrier

; #define PG8_STAGE(bufoff, gbase, voff) do { _Pragma("unroll") for (int _i = 0; _i < 2; ++_i) \
;         __builtin_amdgcn_global_load_lds((const unsigned*)((const char*)(gbase) + (voff)[_i]), (LAS unsigned*)(lds + (bufoff) + ldsw + _i * 8192), 16, 0, 0); } while (0)
; #define PG8_LDA(dst, b, h) do { _Pragma("unroll") for (int m = 0; m < 4; ++m) _Pragma("unroll") for (int k = 0; k < 2; ++k) dst[m][k] = *(const LAS bf16x8*)(lds + PG8_SA(b, h) + aoff + m * 2048 + k * 1024); } while (0)
; #define PG8_LDB(dst, b, h) do { _Pragma("unroll") for (int n = 0; n < 2; ++n) _Pragma("unroll") for (int k = 0; k < 2; ++k) dst[n][k] = *(const LAS bf16x8*)(lds + PG8_SB(b, h) + boff + n * 2048 + k * 1024); } while (0)
; #define PG8_MMA(ai, bj, At, Bt) do { __builtin_amdgcn_s_setprio(1); _Pragma("unroll") for (int m = 0; m < 4; ++m) _Pragma("unroll") for (int n = 0; n < 2; ++n) _Pragma("unroll") for (int k = 0; k < 2; ++k) \
;         acc[ai][bj][m][n] = __builtin_amdgcn_mfma_f32_16x16x32_bf16(Bt[n][k], At[m][k], acc[ai][bj][m][n], 0, 0, 0); __builtin_amdgcn_s_setprio(0); } while (0)
; #define PG8_WAIT_V(n) asm volatile("s_waitcnt vmcnt(" #n ")" ::: "memory")
; #define PG8_WAIT_L(n) asm volatile("s_waitcnt lgkmcnt(" #n ")" ::: "memory")
; #define PG8_BAR __builtin_amdgcn_s_barrier()
; #define PG8_SCHED __builtin_amdgcn_sched_barrier(0)
; template <class Epi, class Sched>
; __device__ __forceinline__ void gemm_phase(LAS unsigned char* lds, const GemmP g, const Sched& S, const Epi& E, int tid) {
;     ...
;         for (int t = 0; t < nt; t += 2) {
;             const bool last = (t == nt - 2);
;             const char* a1 = cA + (size_t)(t + 1) * kstep;
;             const char* a2 = last ? nA : cA + (size_t)(t + 2) * kstep; const char* b2 = last ? nB : cB + (size_t)(t + 2) * kstep;
;             const char* a3 = a2 + kstep; const char* b3 = b2 + kstep;
;             PG8_LDB(B0, 0, 0); PG8_LDB(B1, 0, 1); PG8_SCHED; PG8_LDA(At, 0, 0); PG8_STAGE(PG8_SA(1, 1), a1 + hstepA, voffA);
;             PG8_WAIT_V(8); PG8_WAIT_L(0); PG8_BAR; PG8_MMA(0, 0, At, B0); PG8_MMA(0, 1, At, B1); PG8_BAR; PG8_SCHED;
;             PG8_LDA(At, 0, 1); PG8_STAGE(PG8_SB(0, 0), b2, voffB); PG8_STAGE(PG8_SB(0, 1), b2 + hstepB, voffB); PG8_STAGE(PG8_SA(0, 0), a2, voffA);
.LBB0_1534:
	s_add_u32 s8, s6, 0x100
	s_addc_u32 s9, s7, 0
	s_add_i32 s19, 0, 0x10000
	s_cmp_eq_u32 s18, 40
	s_cselect_b32 s13, s93, s9
	s_cselect_b32 s12, s92, s8
	s_cselect_b32 s11, s95, s17
	s_cselect_b32 s10, s94, s16
	s_add_i32 s20, 0, 0x14000
	v_add_u32_e32 v140, s19, v212
	v_add_u32_e32 v156, s20, v212
	ds_read_b128 v[128:131], v140
	ds_read_b128 v[132:135], v140 offset:1024
	ds_read_b128 v[136:139], v140 offset:2048
	ds_read_b128 v[140:143], v140 offset:3072
	ds_read_b128 v[144:147], v156
	ds_read_b128 v[148:151], v156 offset:1024
	ds_read_b128 v[152:155], v156 offset:2048
	ds_read_b128 v[156:159], v156 offset:3072
	v_lshl_add_u64 v[198:199], s[6:7], 0, v[206:207]
	s_add_i32 m0, s63, 0xc000
	ds_read_b128 v[160:163], v213
	ds_read_b128 v[164:167], v213 offset:1024
	ds_read_b128 v[168:171], v213 offset:2048
	ds_read_b128 v[172:175], v213 offset:3072
	ds_read_b128 v[176:179], v213 offset:4096
	ds_read_b128 v[180:183], v213 offset:5120
	ds_read_b128 v[184:187], v213 offset:6144
	ds_read_b128 v[208:211], v213 offset:7168
	global_load_lds_dwordx4 v[198:199], off
	v_lshl_add_u64 v[198:199], s[6:7], 0, v[194:195]
	s_add_i32 m0, s63, 0xe000
	s_nop 0
	global_load_lds_dwordx4 v[198:199], off
	s_cmp_eq_u32 s18, -2
	s_cbranch_scc1 .Lfirstit_6
	s_waitcnt vmcnt(8)
.Lfirstit_6:
	s_waitcnt lgkmcnt(0)
	s_barrier
	s_setprio 1
	s_waitcnt lgkmcnt(0)
	v_mfma_f32_16x16x32_bf16 v[124:127], v[128:131], v[160:163], v[124:127]
	v_mfma_f32_16x16x32_bf16 v[120:123], v[136:139], v[160:163], v[120:123]
	v_mfma_f32_16x16x32_bf16 v[116:119], v[128:131], v[168:171], v[116:119]
	v_mfma_f32_16x16x32_bf16 v[112:115], v[136:139], v[168:171], v[112:115]
	v_mfma_f32_16x16x32_bf16 v[108:111], v[128:131], v[176:179], v[108:111]
	v_mfma_f32_16x16x32_bf16 v[104:107], v[136:139], v[176:179], v[104:107]
	v_mfma_f32_16x16x32_bf16 v[100:103], v[128:131], v[184:187], v[100:103]
	v_mfma_f32_16x16x32_bf16 v[96:99], v[136:139], v[184:187], v[96:99]
	v_mfma_f32_16x16x32_bf16 v[124:127], v[132:135], v[164:167], v[124:127]
	v_mfma_f32_16x16x32_bf16 v[120:123], v[140:143], v[164:167], v[120:123]
	v_mfma_f32_16x16x32_bf16 v[116:119], v[132:135], v[172:175], v[116:119]
	v_mfma_f32_16x16x32_bf16 v[112:115], v[140:143], v[172:175], v[112:115]
	v_mfma_f32_16x16x32_bf16 v[108:111], v[132:135], v[180:183], v[108:111]
	v_mfma_f32_16x16x32_bf16 v[104:107], v[140:143], v[180:183], v[104:107]
	v_mfma_f32_16x16x32_bf16 v[100:103], v[132:135], v[208:211], v[100:103]
	v_mfma_f32_16x16x32_bf16 v[96:99], v[140:143], v[208:211], v[96:99]
	s_setprio 0
	s_setprio 1
	v_mfma_f32_16x16x32_bf16 v[68:71], v[144:147], v[160:163], v[68:71]
	v_mfma_f32_16x16x32_bf16 v[60:63], v[152:155], v[160:163], v[60:63]
	v_mfma_f32_16x16x32_bf16 v[52:55], v[144:147], v[168:171], v[52:55]
	v_mfma_f32_16x16x32_bf16 v[48:51], v[152:155], v[168:171], v[48:51]
	v_mfma_f32_16x16x32_bf16 v[44:47], v[144:147], v[176:179], v[44:47]
	v_mfma_f32_16x16x32_bf16 v[40:43], v[152:155], v[176:179], v[40:43]
	v_mfma_f32_16x16x32_bf16 v[36:39], v[144:147], v[184:187], v[36:39]
	v_mfma_f32_16x16x32_bf16 v[32:35], v[152:155], v[184:187], v[32:35]
	v_mfma_f32_16x16x32_bf16 v[68:71], v[148:151], v[164:167], v[68:71]
	v_mfma_f32_16x16x32_bf16 v[60:63], v[156:159], v[164:167], v[60:63]
	v_mfma_f32_16x16x32_bf16 v[52:55], v[148:151], v[172:175], v[52:55]
	v_mfma_f32_16x16x32_bf16 v[48:51], v[156:159], v[172:175], v[48:51]
	v_mfma_f32_16x16x32_bf16 v[44:47], v[148:151], v[180:183], v[44:47]
	v_mfma_f32_16x16x32_bf16 v[40:43], v[156:159], v[180:183], v[40:43]
	v_mfma_f32_16x16x32_bf16 v[36:39], v[148:151], v[208:211], v[36:39]
	v_mfma_f32_16x16x32_bf16 v[32:35], v[156:159], v[208:211], v[32:35]
	s_setprio 0
	s_barrier
	s_add_i32 s6, s19, s62
	v_lshl_add_u64 v[198:199], s[10:11], 0, v[196:197]
	s_mov_b32 m0, s6
	ds_read_b128 v[160:163], v213 offset:16384
	ds_read_b128 v[164:167], v213 offset:17408
	ds_read_b128 v[168:171], v213 offset:18432
	ds_read_b128 v[172:175], v213 offset:19456
	ds_read_b128 v[176:179], v213 offset:20480
	ds_read_b128 v[180:183], v213 offset:21504
	ds_read_b128 v[184:187], v213 offset:22528
	ds_read_b128 v[208:211], v213 offset:23552
	global_load_lds_dwordx4 v[198:199], off
	s_add_i32 m0, s6, 0x2000
	s_add_u32 s6, s10, 0xb0000
	v_lshl_add_u64 v[200:201], s[10:11], 0, v[192:193]
	s_addc_u32 s7, s11, 0
	s_add_i32 s19, s20, s62
	global_load_lds_dwordx4 v[200:201], off
	v_lshl_add_u64 v[214:215], s[6:7], 0, v[196:197]
	s_mov_b32 m0, s19
	v_lshl_add_u64 v[216:217], s[12:13], 0, v[190:191]
	global_load_lds_dwordx4 v[214:215], off
	v_lshl_add_u64 v[214:215], s[6:7], 0, v[192:193]
	s_add_i32 m0, s19, 0x2000
	s_nop 0
	global_load_lds_dwordx4 v[214:215], off
	v_lshl_add_u64 v[214:215], s[12:13], 0, v[188:189]
	s_mov_b32 m0, s63
	s_nop 0
	global_load_lds_dwordx4 v[214:215], off
	s_mov_b32 m0, s82
	s_nop 0
	global_load_lds_dwordx4 v[216:217], off
	s_waitcnt vmcnt(8)
	s_waitcnt lgkmcnt(0)
	s_barrier
; #define PG8_STAGE(bufoff, gbase, voff) do { _Pragma("unroll") for (int _i = 0; _i < 2; ++_i) \
;         __builtin_amdgcn_global_load_lds((const unsigned*)((const char*)(gbase) + (voff)[_i]), (LAS unsigned*)(lds + (bufoff) + ldsw + _i * 8192), 16, 0, 0); } while (0)
; #define PG8_LDA(dst, b, h) do { _Pragma("unroll") for (int m = 0; m < 4; ++m) _Pragma("unroll") for (int k = 0; k < 2; ++k) dst[m][k] = *(const LAS bf16x8*)(lds + PG8_SA(b, h) + aoff + m * 2048 + k * 1024); } while (0)
; #define PG8_LDB(dst, b, h) do { _Pragma("unroll") for (int n = 0; n < 2; ++n) _Pragma("unroll") for (int k = 0; k < 2; ++k) dst[n][k] = *(const LAS bf16x8*)(lds + PG8_SB(b, h) + boff + n * 2048 + k * 1024); } while (0)
; #define PG8_MMA(ai, bj, At, Bt) do { __builtin_amdgcn_s_setprio(1); _Pragma("unroll") for (int m = 0; m < 4; ++m) _Pragma("unroll") for (int n = 0; n < 2; ++n) _Pragma("unroll") for (int k = 0; k < 2; ++k) \
;         acc[ai][bj][m][n] = __builtin_amdgcn_mfma_f32_16x16x32_bf16(Bt[n][k], At[m][k], acc[ai][bj][m][n], 0, 0, 0); __builtin_amdgcn_s_setprio(0); } while (0)
; #define PG8_WAIT_V(n) asm volatile("s_waitcnt vmcnt(" #n ")" ::: "memory")
; #define PG8_WAIT_L(n) asm volatile("s_waitcnt lgkmcnt(" #n ")" ::: "memory")
; #define PG8_BAR __builtin_amdgcn_s_barrier()
; #define PG8_SCHED __builtin_amdgcn_sched_barrier(0)
; template <class Epi, class Sched>
; __device__ __forceinline__ void gemm_phase(LAS unsigned char* lds, const GemmP g, const Sched& S, const Epi& E, int tid) {
;     ...
;             PG8_WAIT_V(8); PG8_WAIT_L(0); PG8_BAR; PG8_MMA(1, 0, At, B0); PG8_MMA(1, 1, At, B1); PG8_BAR; PG8_SCHED;
;             PG8_LDB(B0, 1, 0); PG8_LDB(B1, 1, 1); PG8_SCHED; PG8_LDA(At, 1, 0); PG8_STAGE(PG8_SA(0, 1), a2 + hstepA, voffA);
;             PG8_WAIT_V(8); PG8_WAIT_L(0); PG8_BAR; PG8_MMA(0, 0, At, B0); PG8_MMA(0, 1, At, B1); PG8_BAR; PG8_SCHED;
	s_setprio 1
	s_waitcnt lgkmcnt(0)
	v_mfma_f32_16x16x32_bf16 v[92:95], v[128:131], v[160:163], v[92:95]
	v_mfma_f32_16x16x32_bf16 v[88:91], v[136:139], v[160:163], v[88:91]
	v_mfma_f32_16x16x32_bf16 v[84:87], v[128:131], v[168:171], v[84:87]
	v_mfma_f32_16x16x32_bf16 v[80:83], v[136:139], v[168:171], v[80:83]
	v_mfma_f32_16x16x32_bf16 v[76:79], v[128:131], v[176:179], v[76:79]
	v_mfma_f32_16x16x32_bf16 v[72:75], v[136:139], v[176:179], v[72:75]
	v_mfma_f32_16x16x32_bf16 v[64:67], v[128:131], v[184:187], v[64:67]
	v_mfma_f32_16x16x32_bf16 v[56:59], v[136:139], v[184:187], v[56:59]
	v_mfma_f32_16x16x32_bf16 v[92:95], v[132:135], v[164:167], v[92:95]
	v_mfma_f32_16x16x32_bf16 v[88:91], v[140:143], v[164:167], v[88:91]
	v_mfma_f32_16x16x32_bf16 v[84:87], v[132:135], v[172:175], v[84:87]
	v_mfma_f32_16x16x32_bf16 v[80:83], v[140:143], v[172:175], v[80:83]
	v_mfma_f32_16x16x32_bf16 v[76:79], v[132:135], v[180:183], v[76:79]
	v_mfma_f32_16x16x32_bf16 v[72:75], v[140:143], v[180:183], v[72:75]
	v_mfma_f32_16x16x32_bf16 v[64:67], v[132:135], v[208:211], v[64:67]
	v_mfma_f32_16x16x32_bf16 v[56:59], v[140:143], v[208:211], v[56:59]
	s_setprio 0
	s_setprio 1
	v_mfma_f32_16x16x32_bf16 v[28:31], v[144:147], v[160:163], v[28:31]
	v_mfma_f32_16x16x32_bf16 v[24:27], v[152:155], v[160:163], v[24:27]
	v_mfma_f32_16x16x32_bf16 v[20:23], v[144:147], v[168:171], v[20:23]
	v_mfma_f32_16x16x32_bf16 v[16:19], v[152:155], v[168:171], v[16:19]
	v_mfma_f32_16x16x32_bf16 v[12:15], v[144:147], v[176:179], v[12:15]
	v_mfma_f32_16x16x32_bf16 v[8:11], v[152:155], v[176:179], v[8:11]
	v_mfma_f32_16x16x32_bf16 v[4:7], v[144:147], v[184:187], v[4:7]
	v_mfma_f32_16x16x32_bf16 v[0:3], v[152:155], v[184:187], v[0:3]
	v_mfma_f32_16x16x32_bf16 v[28:31], v[148:151], v[164:167], v[28:31]
	v_mfma_f32_16x16x32_bf16 v[24:27], v[156:159], v[164:167], v[24:27]
	v_mfma_f32_16x16x32_bf16 v[20:23], v[148:151], v[172:175], v[20:23]
	v_mfma_f32_16x16x32_bf16 v[16:19], v[156:159], v[172:175], v[16:19]
	v_mfma_f32_16x16x32_bf16 v[12:15], v[148:151], v[180:183], v[12:15]
	v_mfma_f32_16x16x32_bf16 v[8:11], v[156:159], v[180:183], v[8:11]
	v_mfma_f32_16x16x32_bf16 v[4:7], v[148:151], v[208:211], v[4:7]
	v_mfma_f32_16x16x32_bf16 v[0:3], v[156:159], v[208:211], v[0:3]
	s_setprio 0
	s_barrier
	s_add_i32 s19, 0, 0x18000
	s_add_i32 s20, 0, 0x1c000
	v_add_u32_e32 v140, s19, v212
	v_add_u32_e32 v156, s20, v212
	ds_read_b128 v[128:131], v140
	ds_read_b128 v[132:135], v140 offset:1024
	ds_read_b128 v[136:139], v140 offset:2048
	ds_read_b128 v[140:143], v140 offset:3072
	ds_read_b128 v[144:147], v156
	ds_read_b128 v[148:151], v156 offset:1024
	ds_read_b128 v[152:155], v156 offset:2048
	ds_read_b128 v[156:159], v156 offset:3072
	s_add_u32 s6, s12, 0xb0000
	s_addc_u32 s7, s13, 0
	s_mov_b32 m0, s56
	v_lshl_add_u64 v[220:221], s[6:7], 0, v[188:189]
	ds_read_b128 v[160:163], v213 offset:32768
	ds_read_b128 v[164:167], v213 offset:33792
	ds_read_b128 v[168:171], v213 offset:34816
	ds_read_b128 v[172:175], v213 offset:35840
	ds_read_b128 v[176:179], v213 offset:36864
	ds_read_b128 v[180:183], v213 offset:37888
	ds_read_b128 v[184:187], v213 offset:38912
	ds_read_b128 v[208:211], v213 offset:39936
	global_load_lds_dwordx4 v[220:221], off
	v_lshl_add_u64 v[220:221], s[6:7], 0, v[190:191]
	s_mov_b32 m0, s57
	s_nop 0
	global_load_lds_dwordx4 v[220:221], off
	s_waitcnt vmcnt(8)
	s_waitcnt lgkmcnt(0)
	s_barrier
	s_setprio 1
	s_waitcnt lgkmcnt(0)
	v_mfma_f32_16x16x32_bf16 v[124:127], v[128:131], v[160:163], v[124:127]
	v_mfma_f32_16x16x32_bf16 v[120:123], v[136:139], v[160:163], v[120:123]
	v_mfma_f32_16x16x32_bf16 v[116:119], v[128:131], v[168:171], v[116:119]
	v_mfma_f32_16x16x32_bf16 v[112:115], v[136:139], v[168:171], v[112:115]
	v_mfma_f32_16x16x32_bf16 v[108:111], v[128:131], v[176:179], v[108:111]
	v_mfma_f32_16x16x32_bf16 v[104:107], v[136:139], v[176:179], v[104:107]
	v_mfma_f32_16x16x32_bf16 v[100:103], v[128:131], v[184:187], v[100:103]
	v_mfma_f32_16x16x32_bf16 v[96:99], v[136:139], v[184:187], v[96:99]
	v_mfma_f32_16x16x32_bf16 v[124:127], v[132:135], v[164:167], v[124:127]
	v_mfma_f32_16x16x32_bf16 v[120:123], v[140:143], v[164:167], v[120:123]
	v_mfma_f32_16x16x32_bf16 v[116:119], v[132:135], v[172:175], v[116:119]
	v_mfma_f32_16x16x32_bf16 v[112:115], v[140:143], v[172:175], v[112:115]
	v_mfma_f32_16x16x32_bf16 v[108:111], v[132:135], v[180:183], v[108:111]
	v_mfma_f32_16x16x32_bf16 v[104:107], v[140:143], v[180:183], v[104:107]
	v_mfma_f32_16x16x32_bf16 v[100:103], v[132:135], v[208:211], v[100:103]
	v_mfma_f32_16x16x32_bf16 v[96:99], v[140:143], v[208:211], v[96:99]
	s_setprio 0
	s_setprio 1
	v_mfma_f32_16x16x32_bf16 v[68:71], v[144:147], v[160:163], v[68:71]
	v_mfma_f32_16x16x32_bf16 v[60:63], v[152:155], v[160:163], v[60:63]
	v_mfma_f32_16x16x32_bf16 v[52:55], v[144:147], v[168:171], v[52:55]
	v_mfma_f32_16x16x32_bf16 v[48:51], v[152:155], v[168:171], v[48:51]
	v_mfma_f32_16x16x32_bf16 v[44:47], v[144:147], v[176:179], v[44:47]
	v_mfma_f32_16x16x32_bf16 v[40:43], v[152:155], v[176:179], v[40:43]
	v_mfma_f32_16x16x32_bf16 v[36:39], v[144:147], v[184:187], v[36:39]
	v_mfma_f32_16x16x32_bf16 v[32:35], v[152:155], v[184:187], v[32:35]
	v_mfma_f32_16x16x32_bf16 v[68:71], v[148:151], v[164:167], v[68:71]
	v_mfma_f32_16x16x32_bf16 v[60:63], v[156:159], v[164:167], v[60:63]
	v_mfma_f32_16x16x32_bf16 v[52:55], v[148:151], v[172:175], v[52:55]
	v_mfma_f32_16x16x32_bf16 v[48:51], v[156:159], v[172:175], v[48:51]
	v_mfma_f32_16x16x32_bf16 v[44:47], v[148:151], v[180:183], v[44:47]
	v_mfma_f32_16x16x32_bf16 v[40:43], v[156:159], v[180:183], v[40:43]
	v_mfma_f32_16x16x32_bf16 v[36:39], v[148:151], v[208:211], v[36:39]
	v_mfma_f32_16x16x32_bf16 v[32:35], v[156:159], v[208:211], v[32:35]
	s_setprio 0
	s_barrier
; #define PG8_STAGE(bufoff, gbase, voff) do { _Pragma("unroll") for (int _i = 0; _i < 2; ++_i) \
;         __builtin_amdgcn_global_load_lds((const unsigned*)((const char*)(gbase) + (voff)[_i]), (LAS unsigned*)(lds + (bufoff) + ldsw + _i * 8192), 16, 0, 0); } while (0)
; #define PG8_LDA(dst, b, h) do { _Pragma("unroll") for (int m = 0; m < 4; ++m) _Pragma("unroll") for (int k = 0; k < 2; ++k) dst[m][k] = *(const LAS bf16x8*)(lds + PG8_SA(b, h) + aoff + m * 2048 + k * 1024); } while (0)
; #define PG8_MMA(ai, bj, At, Bt) do { __builtin_amdgcn_s_setprio(1); _Pragma("unroll") for (int m = 0; m < 4; ++m) _Pragma("unroll") for (int n = 0; n < 2; ++n) _Pragma("unroll") for (int k = 0; k < 2; ++k) \
;         acc[ai][bj][m][n] = __builtin_amdgcn_mfma_f32_16x16x32_bf16(Bt[n][k], At[m][k], acc[ai][bj][m][n], 0, 0, 0); __builtin_amdgcn_s_setprio(0); } while (0)
; #define PG8_WAIT_V(n) asm volatile("s_waitcnt vmcnt(" #n ")" ::: "memory")
; #define PG8_WAIT_L(n) asm volatile("s_waitcnt lgkmcnt(" #n ")" ::: "memory")
; #define PG8_BAR __builtin_amdgcn_s_barrier()
; #define PG8_SCHED __builtin_amdgcn_sched_barrier(0)
; template <class Epi, class Sched>
; __device__ __forceinline__ void gemm_phase(LAS unsigned char* lds, const GemmP g, const Sched& S, const Epi& E, int tid) {
;     ...
;             PG8_LDA(At, 1, 1); PG8_STAGE(PG8_SB(1, 0), b3, voffB); PG8_STAGE(PG8_SB(1, 1), b3 + hstepB, voffB); PG8_STAGE(PG8_SA(1, 0), a3, voffA);
;             PG8_WAIT_V(8); PG8_WAIT_L(0); PG8_BAR; PG8_MMA(1, 0, At, B0); PG8_MMA(1, 1, At, B1); PG8_BAR; PG8_SCHED;
;         }
;         if (wr == 0) PG8_BAR;
	s_add_i32 s6, s19, s62
	v_lshl_add_u64 v[198:199], v[198:199], 0, s[80:81]
	s_mov_b32 m0, s6
	ds_read_b128 v[160:163], v213 offset:49152
	ds_read_b128 v[164:167], v213 offset:50176
	ds_read_b128 v[168:171], v213 offset:51200
	ds_read_b128 v[172:175], v213 offset:52224
	ds_read_b128 v[176:179], v213 offset:53248
	ds_read_b128 v[180:183], v213 offset:54272
	ds_read_b128 v[184:187], v213 offset:55296
	ds_read_b128 v[208:211], v213 offset:56320
	global_load_lds_dwordx4 v[198:199], off
	s_add_i32 m0, s6, 0x2000
	s_add_u32 s6, s10, 0xb0080
	v_lshl_add_u64 v[198:199], v[200:201], 0, s[80:81]
	s_addc_u32 s7, s11, 0
	s_add_i32 s10, s20, s62
	global_load_lds_dwordx4 v[198:199], off
	v_lshl_add_u64 v[198:199], s[6:7], 0, v[196:197]
	s_mov_b32 m0, s10
	s_nop 0
	global_load_lds_dwordx4 v[198:199], off
	v_lshl_add_u64 v[198:199], s[6:7], 0, v[192:193]
	s_add_i32 m0, s10, 0x2000
	s_nop 0
	global_load_lds_dwordx4 v[198:199], off
	v_lshl_add_u64 v[198:199], v[214:215], 0, s[80:81]
	s_mov_b32 m0, s3
	s_nop 0
	global_load_lds_dwordx4 v[198:199], off
	v_lshl_add_u64 v[198:199], v[216:217], 0, s[80:81]
	s_mov_b32 m0, s44
	s_nop 0
	global_load_lds_dwordx4 v[198:199], off
	s_waitcnt vmcnt(8)
	s_waitcnt lgkmcnt(0)
	s_barrier
	s_setprio 1
	s_waitcnt lgkmcnt(0)
	v_mfma_f32_16x16x32_bf16 v[92:95], v[128:131], v[160:163], v[92:95]
	v_mfma_f32_16x16x32_bf16 v[88:91], v[136:139], v[160:163], v[88:91]
	v_mfma_f32_16x16x32_bf16 v[84:87], v[128:131], v[168:171], v[84:87]
	v_mfma_f32_16x16x32_bf16 v[80:83], v[136:139], v[168:171], v[80:83]
	v_mfma_f32_16x16x32_bf16 v[76:79], v[128:131], v[176:179], v[76:79]
	v_mfma_f32_16x16x32_bf16 v[72:75], v[136:139], v[176:179], v[72:75]
	v_mfma_f32_16x16x32_bf16 v[64:67], v[128:131], v[184:187], v[64:67]
	v_mfma_f32_16x16x32_bf16 v[56:59], v[136:139], v[184:187], v[56:59]
	v_mfma_f32_16x16x32_bf16 v[92:95], v[132:135], v[164:167], v[92:95]
	v_mfma_f32_16x16x32_bf16 v[88:91], v[140:143], v[164:167], v[88:91]
	v_mfma_f32_16x16x32_bf16 v[84:87], v[132:135], v[172:175], v[84:87]
	v_mfma_f32_16x16x32_bf16 v[80:83], v[140:143], v[172:175], v[80:83]
	v_mfma_f32_16x16x32_bf16 v[76:79], v[132:135], v[180:183], v[76:79]
	v_mfma_f32_16x16x32_bf16 v[72:75], v[140:143], v[180:183], v[72:75]
	v_mfma_f32_16x16x32_bf16 v[64:67], v[132:135], v[208:211], v[64:67]
	v_mfma_f32_16x16x32_bf16 v[56:59], v[140:143], v[208:211], v[56:59]
	s_setprio 0
	s_setprio 1
	v_mfma_f32_16x16x32_bf16 v[28:31], v[144:147], v[160:163], v[28:31]
	v_mfma_f32_16x16x32_bf16 v[24:27], v[152:155], v[160:163], v[24:27]
	v_mfma_f32_16x16x32_bf16 v[20:23], v[144:147], v[168:171], v[20:23]
	v_mfma_f32_16x16x32_bf16 v[16:19], v[152:155], v[168:171], v[16:19]
	v_mfma_f32_16x16x32_bf16 v[12:15], v[144:147], v[176:179], v[12:15]
	v_mfma_f32_16x16x32_bf16 v[8:11], v[152:155], v[176:179], v[8:11]
	v_mfma_f32_16x16x32_bf16 v[4:7], v[144:147], v[184:187], v[4:7]
	v_mfma_f32_16x16x32_bf16 v[0:3], v[152:155], v[184:187], v[0:3]
	v_mfma_f32_16x16x32_bf16 v[28:31], v[148:151], v[164:167], v[28:31]
	v_mfma_f32_16x16x32_bf16 v[24:27], v[156:159], v[164:167], v[24:27]
	v_mfma_f32_16x16x32_bf16 v[20:23], v[148:151], v[172:175], v[20:23]
	v_mfma_f32_16x16x32_bf16 v[16:19], v[156:159], v[172:175], v[16:19]
	v_mfma_f32_16x16x32_bf16 v[12:15], v[148:151], v[180:183], v[12:15]
	v_mfma_f32_16x16x32_bf16 v[8:11], v[156:159], v[180:183], v[8:11]
	v_mfma_f32_16x16x32_bf16 v[4:7], v[148:151], v[208:211], v[4:7]
	v_mfma_f32_16x16x32_bf16 v[0:3], v[156:159], v[208:211], v[0:3]
	s_setprio 0
	s_barrier
	s_add_i32 s18, s18, 2
	s_add_u32 s16, s16, 0x100
	s_addc_u32 s17, s17, 0
	s_cmp_gt_u32 s18, 41
	s_mov_b64 s[6:7], s[8:9]
	s_cbranch_scc0 .LBB0_1534
	s_and_b64 vcc, exec, s[86:87]
	s_cbranch_vccz .LBB0_1537
	s_barrier
